# baseline (speedup 1.0000x reference)
; #define PG8_STAGE(bufoff, gbase, voff) do { _Pragma("unroll") for (int _i = 0; _i < 2; ++_i) \
;         __builtin_amdgcn_global_load_lds((const unsigned*)((const char*)(gbase) + (voff)[_i]), (PG8_LAS unsigned*)(lds + (bufoff) + ldsw + _i * 8192), 16, 0, 0); } while (0)
; #define PG8_LDA(dst, b, h) do { _Pragma("unroll") for (int m = 0; m < 4; ++m) _Pragma("unroll") for (int k = 0; k < 2; ++k) dst[m][k] = *(const PG8_LAS bf16x8*)(lds + PG8_SA(b, h) + aoff + m * 2048 + k * 1024); } while (0)
; #define PG8_LDB(dst, b, h) do { _Pragma("unroll") for (int n = 0; n < 2; ++n) _Pragma("unroll") for (int k = 0; k < 2; ++k) dst[n][k] = *(const PG8_LAS bf16x8*)(lds + PG8_SB(b, h) + boff + n * 2048 + k * 1024); } while (0)
; #define PG8_WAIT_V(n) asm volatile("s_waitcnt vmcnt(" #n ")" ::: "memory")
; #define PG8_WAIT_L(n) asm volatile("s_waitcnt lgkmcnt(" #n ")" ::: "memory")
; #define PG8_BAR __builtin_amdgcn_s_barrier()
; #define PG8_SCHED __builtin_amdgcn_sched_barrier(0)
; template <class Epi, class Sched, bool ALIGN_EPI = false, bool SP2 = false>
; __device__ __forceinline__ void gemm_phase(PG8_LAS unsigned char* lds, const Gemm g, const Sched& S, const Epi& E) {
;     ...
;         const char* nA = has_next ? (const char*)g.A + (size_t)nxt.pm * tstep : cA; const char* nB = has_next ? (const char*)g.Bt + (size_t)nxt.pn * tstep : cB;
;         for (int t = 0; t < nt; t += 2) {
;             const bool last = (t == nt - 2);
;             const char* a1 = cA + (size_t)(t + 1) * kstep;
;             const char* a2 = last ? nA : cA + (size_t)(t + 2) * kstep; const char* b2 = last ? nB : cB + (size_t)(t + 2) * kstep;
;             const char* a3 = a2 + kstep; const char* b3 = b2 + kstep;
;             if (last && has_next) S.a_ready(nxt);
;             if constexpr (SP2) {
;             PG8_LDB(B0, 0, 0); PG8_LDB(B1, 0, 1); PG8_SCHED; PG8_LDA(At, 0, 0); PG8_STAGE(PG8_SA(1, 1), a1 + hstep, voffA);
;             PG8_WAIT_V(8); PG8_WAIT_L(0); PG8_BAR; PG8_MMA(0, 0, At, B0); PG8_MMA(0, 1, At, B1); PG8_BAR; PG8_SCHED;
;             PG8_LDA(At, 0, 1); PG8_STAGE(PG8_SB(0, 0), b2, voffB); PG8_STAGE(PG8_SB(0, 1), b2 + hstep, voffB); PG8_STAGE(PG8_SA(0, 0), a2, voffA);
;             PG8_WAIT_V(8); PG8_WAIT_L(0); PG8_BAR; PG8_MMA(1, 0, At, B0); PG8_MMA(1, 1, At, B1); PG8_BAR; PG8_SCHED;
.LBB0_204:
	s_ashr_i32 s61, s60, 31
	s_lshl_b64 s[36:37], s[60:61], 20
	s_add_u32 s62, s45, s36
	s_addc_u32 s63, s44, s37
	s_and_b64 s[36:37], s[6:7], exec
	s_cselect_b32 s9, s63, s69
	s_cselect_b32 s61, s62, s68
	s_ashr_i32 s59, s58, 31
	s_lshl_b64 s[36:37], s[58:59], 20
	s_add_u32 s64, s54, s36
	s_addc_u32 s65, s55, s37
	s_and_b64 s[36:37], s[6:7], exec
	s_cselect_b32 s59, s65, s71
	s_cselect_b32 s87, s64, s70
	s_add_u32 s68, s68, 0x80080
	s_addc_u32 s69, s69, 0
	s_add_u32 s3, s70, 0x100
	s_addc_u32 s88, s71, 0
	s_mov_b32 s89, -2
	s_nop 0
	s_add_u32 s36, s68, 0xfff80080
	s_addc_u32 s37, s69, -1
	s_add_i32 s38, 0, 0x10000
	s_cmp_eq_u32 s89, 28
	s_cselect_b32 s73, s9, s37
	s_cselect_b32 s72, s61, s36
	s_cselect_b32 s71, s59, s88
	s_cselect_b32 s70, s87, s3
	s_add_i32 s39, 0, 0x14000
	s_add_i32 m0, s67, 0xc000
	global_load_lds_dwordx4 v196, s[68:69]
	s_add_i32 m0, s67, 0xe000
	s_nop 0
	global_load_lds_dwordx4 v198, s[68:69]
	s_waitcnt vmcnt(24)
	s_waitcnt lgkmcnt(0)
	s_barrier
	s_setprio 1
	s_waitcnt lgkmcnt(0)
	v_mfma_f32_16x16x32_bf16 v[148:151], v[80:83], v[160:163], 0
	v_mfma_f32_16x16x32_bf16 v[148:151], v[88:91], v[164:167], v[148:151]
	v_mfma_f32_16x16x32_bf16 v[144:147], v[104:107], v[160:163], 0
	v_mfma_f32_16x16x32_bf16 v[144:147], v[108:111], v[164:167], v[144:147]
	v_mfma_f32_16x16x32_bf16 v[124:127], v[80:83], v[168:171], 0
	v_mfma_f32_16x16x32_bf16 v[124:127], v[88:91], v[172:175], v[124:127]
	v_mfma_f32_16x16x32_bf16 v[120:123], v[104:107], v[168:171], 0
	v_mfma_f32_16x16x32_bf16 v[120:123], v[108:111], v[172:175], v[120:123]
	v_mfma_f32_16x16x32_bf16 v[100:103], v[80:83], v[176:179], 0
	v_mfma_f32_16x16x32_bf16 v[100:103], v[88:91], v[180:183], v[100:103]
	v_mfma_f32_16x16x32_bf16 v[96:99], v[104:107], v[176:179], 0
	v_mfma_f32_16x16x32_bf16 v[96:99], v[108:111], v[180:183], v[96:99]
	v_mfma_f32_16x16x32_bf16 v[76:79], v[80:83], v[184:187], 0
	v_mfma_f32_16x16x32_bf16 v[76:79], v[88:91], v[200:203], v[76:79]
	v_mfma_f32_16x16x32_bf16 v[72:75], v[104:107], v[184:187], 0
	v_mfma_f32_16x16x32_bf16 v[72:75], v[108:111], v[200:203], v[72:75]
	v_mfma_f32_16x16x32_bf16 v[140:143], v[128:131], v[160:163], 0
	v_mfma_f32_16x16x32_bf16 v[140:143], v[132:135], v[164:167], v[140:143]
	v_mfma_f32_16x16x32_bf16 v[136:139], v[152:155], v[160:163], 0
	v_mfma_f32_16x16x32_bf16 v[136:139], v[156:159], v[164:167], v[136:139]
	v_mfma_f32_16x16x32_bf16 v[116:119], v[128:131], v[168:171], 0
	v_mfma_f32_16x16x32_bf16 v[116:119], v[132:135], v[172:175], v[116:119]
	v_mfma_f32_16x16x32_bf16 v[112:115], v[152:155], v[168:171], 0
	v_mfma_f32_16x16x32_bf16 v[112:115], v[156:159], v[172:175], v[112:115]
	v_mfma_f32_16x16x32_bf16 v[92:95], v[128:131], v[176:179], 0
	v_mfma_f32_16x16x32_bf16 v[92:95], v[132:135], v[180:183], v[92:95]
	v_mfma_f32_16x16x32_bf16 v[84:87], v[152:155], v[176:179], 0
	v_mfma_f32_16x16x32_bf16 v[84:87], v[156:159], v[180:183], v[84:87]
	v_mfma_f32_16x16x32_bf16 v[68:71], v[128:131], v[184:187], 0
	v_mfma_f32_16x16x32_bf16 v[68:71], v[132:135], v[200:203], v[68:71]
	v_mfma_f32_16x16x32_bf16 v[64:67], v[152:155], v[184:187], 0
	v_mfma_f32_16x16x32_bf16 v[64:67], v[156:159], v[200:203], v[64:67]
	s_setprio 0
	s_barrier
	s_add_i32 s36, s38, s75
	s_mov_b32 m0, s36
	ds_read_b128 v[160:163], v240 offset:16384
	ds_read_b128 v[164:167], v240 offset:17408
	ds_read_b128 v[168:171], v240 offset:18432
	ds_read_b128 v[172:175], v240 offset:19456
	ds_read_b128 v[176:179], v240 offset:20480
	ds_read_b128 v[180:183], v240 offset:21504
	ds_read_b128 v[184:187], v240 offset:22528
	ds_read_b128 v[200:203], v240 offset:23552
	global_load_lds_dwordx4 v188, s[70:71]
	s_add_i32 m0, s36, 0x2000
	s_add_u32 s36, s70, 0x80000
	s_addc_u32 s37, s71, 0
	s_add_i32 s38, s39, s75
	global_load_lds_dwordx4 v194, s[70:71]
	s_mov_b32 m0, s38
	s_nop 0
	global_load_lds_dwordx4 v188, s[36:37]
	s_add_i32 m0, s38, 0x2000
	s_nop 0
	global_load_lds_dwordx4 v194, s[36:37]
	s_mov_b32 m0, s67
	s_nop 0
	global_load_lds_dwordx4 v188, s[72:73]
	s_mov_b32 m0, s76
	s_nop 0
	global_load_lds_dwordx4 v194, s[72:73]
	s_waitcnt vmcnt(24)
	s_waitcnt lgkmcnt(0)
	s_barrier
	s_setprio 1
	s_waitcnt lgkmcnt(0)
	v_mfma_f32_16x16x32_bf16 v[60:63], v[80:83], v[160:163], 0
	v_mfma_f32_16x16x32_bf16 v[60:63], v[88:91], v[164:167], v[60:63]
	v_mfma_f32_16x16x32_bf16 v[56:59], v[104:107], v[160:163], 0
	v_mfma_f32_16x16x32_bf16 v[56:59], v[108:111], v[164:167], v[56:59]
	v_mfma_f32_16x16x32_bf16 v[44:47], v[80:83], v[168:171], 0
	v_mfma_f32_16x16x32_bf16 v[44:47], v[88:91], v[172:175], v[44:47]
	v_mfma_f32_16x16x32_bf16 v[40:43], v[104:107], v[168:171], 0
	v_mfma_f32_16x16x32_bf16 v[40:43], v[108:111], v[172:175], v[40:43]
	v_mfma_f32_16x16x32_bf16 v[28:31], v[80:83], v[176:179], 0
	v_mfma_f32_16x16x32_bf16 v[28:31], v[88:91], v[180:183], v[28:31]
	v_mfma_f32_16x16x32_bf16 v[24:27], v[104:107], v[176:179], 0
	v_mfma_f32_16x16x32_bf16 v[24:27], v[108:111], v[180:183], v[24:27]
	v_mfma_f32_16x16x32_bf16 v[12:15], v[80:83], v[184:187], 0
	v_mfma_f32_16x16x32_bf16 v[12:15], v[88:91], v[200:203], v[12:15]
	v_mfma_f32_16x16x32_bf16 v[8:11], v[104:107], v[184:187], 0
	v_mfma_f32_16x16x32_bf16 v[8:11], v[108:111], v[200:203], v[8:11]
	v_mfma_f32_16x16x32_bf16 v[52:55], v[128:131], v[160:163], 0
	v_mfma_f32_16x16x32_bf16 v[52:55], v[132:135], v[164:167], v[52:55]
	v_mfma_f32_16x16x32_bf16 v[48:51], v[152:155], v[160:163], 0
	v_mfma_f32_16x16x32_bf16 v[48:51], v[156:159], v[164:167], v[48:51]
	v_mfma_f32_16x16x32_bf16 v[36:39], v[128:131], v[168:171], 0
	v_mfma_f32_16x16x32_bf16 v[36:39], v[132:135], v[172:175], v[36:39]
	v_mfma_f32_16x16x32_bf16 v[32:35], v[152:155], v[168:171], 0
	v_mfma_f32_16x16x32_bf16 v[32:35], v[156:159], v[172:175], v[32:35]
	v_mfma_f32_16x16x32_bf16 v[20:23], v[128:131], v[176:179], 0
	v_mfma_f32_16x16x32_bf16 v[20:23], v[132:135], v[180:183], v[20:23]
	v_mfma_f32_16x16x32_bf16 v[16:19], v[152:155], v[176:179], 0
	v_mfma_f32_16x16x32_bf16 v[16:19], v[156:159], v[180:183], v[16:19]
	v_mfma_f32_16x16x32_bf16 v[4:7], v[128:131], v[184:187], 0
	v_mfma_f32_16x16x32_bf16 v[4:7], v[132:135], v[200:203], v[4:7]
	v_mfma_f32_16x16x32_bf16 v[0:3], v[152:155], v[184:187], 0
	v_mfma_f32_16x16x32_bf16 v[0:3], v[156:159], v[200:203], v[0:3]
	s_setprio 0
	s_barrier
; #define PG8_STAGE(bufoff, gbase, voff) do { _Pragma("unroll") for (int _i = 0; _i < 2; ++_i) \
;         __builtin_amdgcn_global_load_lds((const unsigned*)((const char*)(gbase) + (voff)[_i]), (PG8_LAS unsigned*)(lds + (bufoff) + ldsw + _i * 8192), 16, 0, 0); } while (0)
; #define PG8_LDA(dst, b, h) do { _Pragma("unroll") for (int m = 0; m < 4; ++m) _Pragma("unroll") for (int k = 0; k < 2; ++k) dst[m][k] = *(const PG8_LAS bf16x8*)(lds + PG8_SA(b, h) + aoff + m * 2048 + k * 1024); } while (0)
; #define PG8_LDB(dst, b, h) do { _Pragma("unroll") for (int n = 0; n < 2; ++n) _Pragma("unroll") for (int k = 0; k < 2; ++k) dst[n][k] = *(const PG8_LAS bf16x8*)(lds + PG8_SB(b, h) + boff + n * 2048 + k * 1024); } while (0)
; #define PG8_MMA(ai, bj, At, Bt) do { __builtin_amdgcn_s_setprio(1); _Pragma("unroll") for (int m = 0; m < 4; ++m) _Pragma("unroll") for (int n = 0; n < 2; ++n) _Pragma("unroll") for (int k = 0; k < 2; ++k) \
;         acc[ai][bj][m][n] = __builtin_amdgcn_mfma_f32_16x16x32_bf16(Bt[n][k], At[m][k], acc[ai][bj][m][n], 0, 0, 0); __builtin_amdgcn_s_setprio(0); } while (0)
; #define PG8_WAIT_V(n) asm volatile("s_waitcnt vmcnt(" #n ")" ::: "memory")
; #define PG8_WAIT_L(n) asm volatile("s_waitcnt lgkmcnt(" #n ")" ::: "memory")
; #define PG8_BAR __builtin_amdgcn_s_barrier()
; #define PG8_SCHED __builtin_amdgcn_sched_barrier(0)
; template <class Epi, class Sched, bool ALIGN_EPI = false, bool SP2 = false>
; __device__ __forceinline__ void gemm_phase(PG8_LAS unsigned char* lds, const Gemm g, const Sched& S, const Epi& E) {
;     ...
;             PG8_LDB(B0, 1, 0); PG8_LDB(B1, 1, 1); PG8_SCHED; PG8_LDA(At, 1, 0); PG8_STAGE(PG8_SA(0, 1), a2 + hstep, voffA);
;             PG8_WAIT_V(8); PG8_WAIT_L(0); PG8_BAR; PG8_MMA(0, 0, At, B0); PG8_MMA(0, 1, At, B1); PG8_BAR; PG8_SCHED;
;             PG8_LDA(At, 1, 1); PG8_STAGE(PG8_SB(1, 0), b3, voffB); PG8_STAGE(PG8_SB(1, 1), b3 + hstep, voffB); PG8_STAGE(PG8_SA(1, 0), a3, voffA);
;             PG8_WAIT_V(8); PG8_WAIT_L(0); PG8_BAR; PG8_MMA(1, 0, At, B0); PG8_MMA(1, 1, At, B1); PG8_BAR; PG8_SCHED;
	s_add_i32 s38, 0, 0x18000
	s_add_i32 s39, 0, 0x1c000
	ds_read_b128 v[80:83], v204 offset:32768
	ds_read_b128 v[88:91], v204 offset:33792
	ds_read_b128 v[104:107], v204 offset:34816
	ds_read_b128 v[108:111], v204 offset:35840
	ds_read_b128 v[128:131], v204 offset:49152
	ds_read_b128 v[132:135], v204 offset:50176
	ds_read_b128 v[152:155], v204 offset:51200
	ds_read_b128 v[156:159], v204 offset:52224
	s_add_u32 s36, s72, 0x80000
	s_addc_u32 s37, s73, 0
	s_mov_b32 m0, s77
	ds_read_b128 v[160:163], v240 offset:32768
	ds_read_b128 v[164:167], v240 offset:33792
	ds_read_b128 v[168:171], v240 offset:34816
	ds_read_b128 v[172:175], v240 offset:35840
	ds_read_b128 v[176:179], v240 offset:36864
	ds_read_b128 v[180:183], v240 offset:37888
	ds_read_b128 v[184:187], v240 offset:38912
	ds_read_b128 v[200:203], v240 offset:39936
	global_load_lds_dwordx4 v188, s[36:37]
	s_mov_b32 m0, s78
	s_nop 0
	global_load_lds_dwordx4 v194, s[36:37]
	s_waitcnt vmcnt(8)
	s_waitcnt lgkmcnt(0)
	s_barrier
	s_setprio 1
	s_waitcnt lgkmcnt(0)
	v_mfma_f32_16x16x32_bf16 v[148:151], v[80:83], v[160:163], v[148:151]
	v_mfma_f32_16x16x32_bf16 v[148:151], v[88:91], v[164:167], v[148:151]
	v_mfma_f32_16x16x32_bf16 v[144:147], v[104:107], v[160:163], v[144:147]
	v_mfma_f32_16x16x32_bf16 v[144:147], v[108:111], v[164:167], v[144:147]
	v_mfma_f32_16x16x32_bf16 v[124:127], v[80:83], v[168:171], v[124:127]
	v_mfma_f32_16x16x32_bf16 v[124:127], v[88:91], v[172:175], v[124:127]
	v_mfma_f32_16x16x32_bf16 v[120:123], v[104:107], v[168:171], v[120:123]
	v_mfma_f32_16x16x32_bf16 v[120:123], v[108:111], v[172:175], v[120:123]
	v_mfma_f32_16x16x32_bf16 v[100:103], v[80:83], v[176:179], v[100:103]
	v_mfma_f32_16x16x32_bf16 v[100:103], v[88:91], v[180:183], v[100:103]
	v_mfma_f32_16x16x32_bf16 v[96:99], v[104:107], v[176:179], v[96:99]
	v_mfma_f32_16x16x32_bf16 v[96:99], v[108:111], v[180:183], v[96:99]
	v_mfma_f32_16x16x32_bf16 v[76:79], v[80:83], v[184:187], v[76:79]
	v_mfma_f32_16x16x32_bf16 v[76:79], v[88:91], v[200:203], v[76:79]
	v_mfma_f32_16x16x32_bf16 v[72:75], v[104:107], v[184:187], v[72:75]
	v_mfma_f32_16x16x32_bf16 v[72:75], v[108:111], v[200:203], v[72:75]
	v_mfma_f32_16x16x32_bf16 v[140:143], v[128:131], v[160:163], v[140:143]
	v_mfma_f32_16x16x32_bf16 v[140:143], v[132:135], v[164:167], v[140:143]
	v_mfma_f32_16x16x32_bf16 v[136:139], v[152:155], v[160:163], v[136:139]
	v_mfma_f32_16x16x32_bf16 v[136:139], v[156:159], v[164:167], v[136:139]
	v_mfma_f32_16x16x32_bf16 v[116:119], v[128:131], v[168:171], v[116:119]
	v_mfma_f32_16x16x32_bf16 v[116:119], v[132:135], v[172:175], v[116:119]
	v_mfma_f32_16x16x32_bf16 v[112:115], v[152:155], v[168:171], v[112:115]
	v_mfma_f32_16x16x32_bf16 v[112:115], v[156:159], v[172:175], v[112:115]
	v_mfma_f32_16x16x32_bf16 v[92:95], v[128:131], v[176:179], v[92:95]
	v_mfma_f32_16x16x32_bf16 v[92:95], v[132:135], v[180:183], v[92:95]
	v_mfma_f32_16x16x32_bf16 v[84:87], v[152:155], v[176:179], v[84:87]
	v_mfma_f32_16x16x32_bf16 v[84:87], v[156:159], v[180:183], v[84:87]
	v_mfma_f32_16x16x32_bf16 v[68:71], v[128:131], v[184:187], v[68:71]
	v_mfma_f32_16x16x32_bf16 v[68:71], v[132:135], v[200:203], v[68:71]
	v_mfma_f32_16x16x32_bf16 v[64:67], v[152:155], v[184:187], v[64:67]
	v_mfma_f32_16x16x32_bf16 v[64:67], v[156:159], v[200:203], v[64:67]
	s_setprio 0
	s_barrier
	s_add_i32 s36, s38, s75
	s_mov_b32 m0, s36
	ds_read_b128 v[160:163], v240 offset:49152
	ds_read_b128 v[164:167], v240 offset:50176
	ds_read_b128 v[168:171], v240 offset:51200
	ds_read_b128 v[172:175], v240 offset:52224
	ds_read_b128 v[176:179], v240 offset:53248
	ds_read_b128 v[180:183], v240 offset:54272
	ds_read_b128 v[184:187], v240 offset:55296
	ds_read_b128 v[200:203], v240 offset:56320
	s_add_u32 s100, s70, 0x80
	s_addc_u32 s101, s71, 0
	global_load_lds_dwordx4 v188, s[100:101]
	s_add_i32 m0, s36, 0x2000
	s_add_u32 s36, s70, 0x80080
	s_addc_u32 s37, s71, 0
	s_add_i32 s38, s39, s75
	global_load_lds_dwordx4 v194, s[100:101]
	s_mov_b32 m0, s38
	s_nop 0
	global_load_lds_dwordx4 v188, s[36:37]
	s_add_i32 m0, s38, 0x2000
	s_nop 0
	global_load_lds_dwordx4 v194, s[36:37]
	s_mov_b32 m0, s79
	s_nop 0
	s_add_u32 s100, s72, 0x80
	s_addc_u32 s101, s73, 0
	global_load_lds_dwordx4 v188, s[100:101]
	s_mov_b32 m0, s80
	s_nop 0
	global_load_lds_dwordx4 v194, s[100:101]
	s_waitcnt vmcnt(8)
	s_waitcnt lgkmcnt(0)
	s_barrier
	s_setprio 1
	s_waitcnt lgkmcnt(0)
	v_mfma_f32_16x16x32_bf16 v[60:63], v[80:83], v[160:163], v[60:63]
	v_mfma_f32_16x16x32_bf16 v[60:63], v[88:91], v[164:167], v[60:63]
	v_mfma_f32_16x16x32_bf16 v[56:59], v[104:107], v[160:163], v[56:59]
	v_mfma_f32_16x16x32_bf16 v[56:59], v[108:111], v[164:167], v[56:59]
	v_mfma_f32_16x16x32_bf16 v[44:47], v[80:83], v[168:171], v[44:47]
	v_mfma_f32_16x16x32_bf16 v[44:47], v[88:91], v[172:175], v[44:47]
	v_mfma_f32_16x16x32_bf16 v[40:43], v[104:107], v[168:171], v[40:43]
	v_mfma_f32_16x16x32_bf16 v[40:43], v[108:111], v[172:175], v[40:43]
	v_mfma_f32_16x16x32_bf16 v[28:31], v[80:83], v[176:179], v[28:31]
	v_mfma_f32_16x16x32_bf16 v[28:31], v[88:91], v[180:183], v[28:31]
	v_mfma_f32_16x16x32_bf16 v[24:27], v[104:107], v[176:179], v[24:27]
	v_mfma_f32_16x16x32_bf16 v[24:27], v[108:111], v[180:183], v[24:27]
	v_mfma_f32_16x16x32_bf16 v[12:15], v[80:83], v[184:187], v[12:15]
	v_mfma_f32_16x16x32_bf16 v[12:15], v[88:91], v[200:203], v[12:15]
	v_mfma_f32_16x16x32_bf16 v[8:11], v[104:107], v[184:187], v[8:11]
	v_mfma_f32_16x16x32_bf16 v[8:11], v[108:111], v[200:203], v[8:11]
	v_mfma_f32_16x16x32_bf16 v[52:55], v[128:131], v[160:163], v[52:55]
	v_mfma_f32_16x16x32_bf16 v[52:55], v[132:135], v[164:167], v[52:55]
	v_mfma_f32_16x16x32_bf16 v[48:51], v[152:155], v[160:163], v[48:51]
	v_mfma_f32_16x16x32_bf16 v[48:51], v[156:159], v[164:167], v[48:51]
	v_mfma_f32_16x16x32_bf16 v[36:39], v[128:131], v[168:171], v[36:39]
	v_mfma_f32_16x16x32_bf16 v[36:39], v[132:135], v[172:175], v[36:39]
	v_mfma_f32_16x16x32_bf16 v[32:35], v[152:155], v[168:171], v[32:35]
	v_mfma_f32_16x16x32_bf16 v[32:35], v[156:159], v[172:175], v[32:35]
	v_mfma_f32_16x16x32_bf16 v[20:23], v[128:131], v[176:179], v[20:23]
	v_mfma_f32_16x16x32_bf16 v[20:23], v[132:135], v[180:183], v[20:23]
	v_mfma_f32_16x16x32_bf16 v[16:19], v[152:155], v[176:179], v[16:19]
	v_mfma_f32_16x16x32_bf16 v[16:19], v[156:159], v[180:183], v[16:19]
	v_mfma_f32_16x16x32_bf16 v[4:7], v[128:131], v[184:187], v[4:7]
	v_mfma_f32_16x16x32_bf16 v[4:7], v[132:135], v[200:203], v[4:7]
	v_mfma_f32_16x16x32_bf16 v[0:3], v[152:155], v[184:187], v[0:3]
	v_mfma_f32_16x16x32_bf16 v[0:3], v[156:159], v[200:203], v[0:3]
	s_setprio 0
	s_barrier
	s_add_i32 s89, s89, 2
	s_add_u32 s68, s68, 0x100
	s_addc_u32 s69, s69, 0
	s_add_u32 s3, s3, 0x100
	s_addc_u32 s88, s88, 0
	s_cmp_gt_u32 s89, 29
; #define PG8_STAGE(bufoff, gbase, voff) do { _Pragma("unroll") for (int _i = 0; _i < 2; ++_i) \
;         __builtin_amdgcn_global_load_lds((const unsigned*)((const char*)(gbase) + (voff)[_i]), (PG8_LAS unsigned*)(lds + (bufoff) + ldsw + _i * 8192), 16, 0, 0); } while (0)
; #define PG8_LDA(dst, b, h) do { _Pragma("unroll") for (int m = 0; m < 4; ++m) _Pragma("unroll") for (int k = 0; k < 2; ++k) dst[m][k] = *(const PG8_LAS bf16x8*)(lds + PG8_SA(b, h) + aoff + m * 2048 + k * 1024); } while (0)
; #define PG8_LDB(dst, b, h) do { _Pragma("unroll") for (int n = 0; n < 2; ++n) _Pragma("unroll") for (int k = 0; k < 2; ++k) dst[n][k] = *(const PG8_LAS bf16x8*)(lds + PG8_SB(b, h) + boff + n * 2048 + k * 1024); } while (0)
; #define PG8_MMA(ai, bj, At, Bt) do { __builtin_amdgcn_s_setprio(1); _Pragma("unroll") for (int m = 0; m < 4; ++m) _Pragma("unroll") for (int n = 0; n < 2; ++n) _Pragma("unroll") for (int k = 0; k < 2; ++k) \
;         acc[ai][bj][m][n] = __builtin_amdgcn_mfma_f32_16x16x32_bf16(Bt[n][k], At[m][k], acc[ai][bj][m][n], 0, 0, 0); __builtin_amdgcn_s_setprio(0); } while (0)
; #define PG8_WAIT_V(n) asm volatile("s_waitcnt vmcnt(" #n ")" ::: "memory")
; #define PG8_WAIT_L(n) asm volatile("s_waitcnt lgkmcnt(" #n ")" ::: "memory")
; #define PG8_BAR __builtin_amdgcn_s_barrier()
; #define PG8_SCHED __builtin_amdgcn_sched_barrier(0)
; template <class Epi, class Sched, bool ALIGN_EPI = false, bool SP2 = false>
; __device__ __forceinline__ void gemm_phase(PG8_LAS unsigned char* lds, const Gemm g, const Sched& S, const Epi& E) {
;     ...
;             PG8_LDB(B0, 0, 0); PG8_LDB(B1, 0, 1); PG8_SCHED; PG8_LDA(At, 0, 0); PG8_STAGE(PG8_SA(1, 1), a1 + hstep, voffA);
;             PG8_WAIT_V(8); PG8_WAIT_L(0); PG8_BAR; PG8_MMA(0, 0, At, B0); PG8_MMA(0, 1, At, B1); PG8_BAR; PG8_SCHED;
;             PG8_LDA(At, 0, 1); PG8_STAGE(PG8_SB(0, 0), b2, voffB); PG8_STAGE(PG8_SB(0, 1), b2 + hstep, voffB); PG8_STAGE(PG8_SA(0, 0), a2, voffA);
;             PG8_WAIT_V(8); PG8_WAIT_L(0); PG8_BAR; PG8_MMA(1, 0, At, B0); PG8_MMA(1, 1, At, B1); PG8_BAR; PG8_SCHED;
.LBB0_205:
	s_add_u32 s36, s68, 0xfff80080
	s_addc_u32 s37, s69, -1
	s_add_i32 s38, 0, 0x10000
	s_cmp_eq_u32 s89, 28
	s_cselect_b32 s73, s9, s37
	s_cselect_b32 s72, s61, s36
	s_cselect_b32 s71, s59, s88
	s_cselect_b32 s70, s87, s3
	s_add_i32 s39, 0, 0x14000
	ds_read_b128 v[80:83], v204
	ds_read_b128 v[88:91], v204 offset:1024
	ds_read_b128 v[104:107], v204 offset:2048
	ds_read_b128 v[108:111], v204 offset:3072
	ds_read_b128 v[128:131], v204 offset:16384
	ds_read_b128 v[132:135], v204 offset:17408
	ds_read_b128 v[152:155], v204 offset:18432
	ds_read_b128 v[156:159], v204 offset:19456
	s_add_i32 m0, s67, 0xc000
	ds_read_b128 v[160:163], v240
	ds_read_b128 v[164:167], v240 offset:1024
	ds_read_b128 v[168:171], v240 offset:2048
	ds_read_b128 v[172:175], v240 offset:3072
	ds_read_b128 v[176:179], v240 offset:4096
	ds_read_b128 v[180:183], v240 offset:5120
	ds_read_b128 v[184:187], v240 offset:6144
	ds_read_b128 v[200:203], v240 offset:7168
	global_load_lds_dwordx4 v196, s[68:69]
	s_add_i32 m0, s67, 0xe000
	s_nop 0
	global_load_lds_dwordx4 v198, s[68:69]
	s_waitcnt vmcnt(8)
	s_waitcnt lgkmcnt(0)
	s_barrier
	s_setprio 1
	s_waitcnt lgkmcnt(0)
	v_mfma_f32_16x16x32_bf16 v[148:151], v[80:83], v[160:163], v[148:151]
	v_mfma_f32_16x16x32_bf16 v[148:151], v[88:91], v[164:167], v[148:151]
	v_mfma_f32_16x16x32_bf16 v[144:147], v[104:107], v[160:163], v[144:147]
	v_mfma_f32_16x16x32_bf16 v[144:147], v[108:111], v[164:167], v[144:147]
	v_mfma_f32_16x16x32_bf16 v[124:127], v[80:83], v[168:171], v[124:127]
	v_mfma_f32_16x16x32_bf16 v[124:127], v[88:91], v[172:175], v[124:127]
	v_mfma_f32_16x16x32_bf16 v[120:123], v[104:107], v[168:171], v[120:123]
	v_mfma_f32_16x16x32_bf16 v[120:123], v[108:111], v[172:175], v[120:123]
	v_mfma_f32_16x16x32_bf16 v[100:103], v[80:83], v[176:179], v[100:103]
	v_mfma_f32_16x16x32_bf16 v[100:103], v[88:91], v[180:183], v[100:103]
	v_mfma_f32_16x16x32_bf16 v[96:99], v[104:107], v[176:179], v[96:99]
	v_mfma_f32_16x16x32_bf16 v[96:99], v[108:111], v[180:183], v[96:99]
	v_mfma_f32_16x16x32_bf16 v[76:79], v[80:83], v[184:187], v[76:79]
	v_mfma_f32_16x16x32_bf16 v[76:79], v[88:91], v[200:203], v[76:79]
	v_mfma_f32_16x16x32_bf16 v[72:75], v[104:107], v[184:187], v[72:75]
	v_mfma_f32_16x16x32_bf16 v[72:75], v[108:111], v[200:203], v[72:75]
	v_mfma_f32_16x16x32_bf16 v[140:143], v[128:131], v[160:163], v[140:143]
	v_mfma_f32_16x16x32_bf16 v[140:143], v[132:135], v[164:167], v[140:143]
	v_mfma_f32_16x16x32_bf16 v[136:139], v[152:155], v[160:163], v[136:139]
	v_mfma_f32_16x16x32_bf16 v[136:139], v[156:159], v[164:167], v[136:139]
	v_mfma_f32_16x16x32_bf16 v[116:119], v[128:131], v[168:171], v[116:119]
	v_mfma_f32_16x16x32_bf16 v[116:119], v[132:135], v[172:175], v[116:119]
	v_mfma_f32_16x16x32_bf16 v[112:115], v[152:155], v[168:171], v[112:115]
	v_mfma_f32_16x16x32_bf16 v[112:115], v[156:159], v[172:175], v[112:115]
	v_mfma_f32_16x16x32_bf16 v[92:95], v[128:131], v[176:179], v[92:95]
	v_mfma_f32_16x16x32_bf16 v[92:95], v[132:135], v[180:183], v[92:95]
	v_mfma_f32_16x16x32_bf16 v[84:87], v[152:155], v[176:179], v[84:87]
	v_mfma_f32_16x16x32_bf16 v[84:87], v[156:159], v[180:183], v[84:87]
	v_mfma_f32_16x16x32_bf16 v[68:71], v[128:131], v[184:187], v[68:71]
	v_mfma_f32_16x16x32_bf16 v[68:71], v[132:135], v[200:203], v[68:71]
	v_mfma_f32_16x16x32_bf16 v[64:67], v[152:155], v[184:187], v[64:67]
	v_mfma_f32_16x16x32_bf16 v[64:67], v[156:159], v[200:203], v[64:67]
	s_setprio 0
	s_barrier
	s_add_i32 s36, s38, s75
	s_mov_b32 m0, s36
	ds_read_b128 v[160:163], v240 offset:16384
	ds_read_b128 v[164:167], v240 offset:17408
	ds_read_b128 v[168:171], v240 offset:18432
	ds_read_b128 v[172:175], v240 offset:19456
	ds_read_b128 v[176:179], v240 offset:20480
	ds_read_b128 v[180:183], v240 offset:21504
	ds_read_b128 v[184:187], v240 offset:22528
	ds_read_b128 v[200:203], v240 offset:23552
	global_load_lds_dwordx4 v188, s[70:71]
	s_add_i32 m0, s36, 0x2000
	s_add_u32 s36, s70, 0x80000
	s_addc_u32 s37, s71, 0
	s_add_i32 s38, s39, s75
	global_load_lds_dwordx4 v194, s[70:71]
	s_mov_b32 m0, s38
	s_nop 0
	global_load_lds_dwordx4 v188, s[36:37]
	s_add_i32 m0, s38, 0x2000
	s_nop 0
	global_load_lds_dwordx4 v194, s[36:37]
	s_mov_b32 m0, s67
	s_nop 0
	global_load_lds_dwordx4 v188, s[72:73]
	s_mov_b32 m0, s76
	s_nop 0
	global_load_lds_dwordx4 v194, s[72:73]
	s_waitcnt vmcnt(8)
	s_waitcnt lgkmcnt(0)
	s_barrier
	s_setprio 1
	s_waitcnt lgkmcnt(0)
	v_mfma_f32_16x16x32_bf16 v[60:63], v[80:83], v[160:163], v[60:63]
	v_mfma_f32_16x16x32_bf16 v[60:63], v[88:91], v[164:167], v[60:63]
	v_mfma_f32_16x16x32_bf16 v[56:59], v[104:107], v[160:163], v[56:59]
	v_mfma_f32_16x16x32_bf16 v[56:59], v[108:111], v[164:167], v[56:59]
	v_mfma_f32_16x16x32_bf16 v[44:47], v[80:83], v[168:171], v[44:47]
	v_mfma_f32_16x16x32_bf16 v[44:47], v[88:91], v[172:175], v[44:47]
	v_mfma_f32_16x16x32_bf16 v[40:43], v[104:107], v[168:171], v[40:43]
	v_mfma_f32_16x16x32_bf16 v[40:43], v[108:111], v[172:175], v[40:43]
	v_mfma_f32_16x16x32_bf16 v[28:31], v[80:83], v[176:179], v[28:31]
	v_mfma_f32_16x16x32_bf16 v[28:31], v[88:91], v[180:183], v[28:31]
	v_mfma_f32_16x16x32_bf16 v[24:27], v[104:107], v[176:179], v[24:27]
	v_mfma_f32_16x16x32_bf16 v[24:27], v[108:111], v[180:183], v[24:27]
	v_mfma_f32_16x16x32_bf16 v[12:15], v[80:83], v[184:187], v[12:15]
	v_mfma_f32_16x16x32_bf16 v[12:15], v[88:91], v[200:203], v[12:15]
	v_mfma_f32_16x16x32_bf16 v[8:11], v[104:107], v[184:187], v[8:11]
	v_mfma_f32_16x16x32_bf16 v[8:11], v[108:111], v[200:203], v[8:11]
	v_mfma_f32_16x16x32_bf16 v[52:55], v[128:131], v[160:163], v[52:55]
	v_mfma_f32_16x16x32_bf16 v[52:55], v[132:135], v[164:167], v[52:55]
	v_mfma_f32_16x16x32_bf16 v[48:51], v[152:155], v[160:163], v[48:51]
	v_mfma_f32_16x16x32_bf16 v[48:51], v[156:159], v[164:167], v[48:51]
	v_mfma_f32_16x16x32_bf16 v[36:39], v[128:131], v[168:171], v[36:39]
	v_mfma_f32_16x16x32_bf16 v[36:39], v[132:135], v[172:175], v[36:39]
	v_mfma_f32_16x16x32_bf16 v[32:35], v[152:155], v[168:171], v[32:35]
	v_mfma_f32_16x16x32_bf16 v[32:35], v[156:159], v[172:175], v[32:35]
	v_mfma_f32_16x16x32_bf16 v[20:23], v[128:131], v[176:179], v[20:23]
	v_mfma_f32_16x16x32_bf16 v[20:23], v[132:135], v[180:183], v[20:23]
	v_mfma_f32_16x16x32_bf16 v[16:19], v[152:155], v[176:179], v[16:19]
	v_mfma_f32_16x16x32_bf16 v[16:19], v[156:159], v[180:183], v[16:19]
	v_mfma_f32_16x16x32_bf16 v[4:7], v[128:131], v[184:187], v[4:7]
	v_mfma_f32_16x16x32_bf16 v[4:7], v[132:135], v[200:203], v[4:7]
	v_mfma_f32_16x16x32_bf16 v[0:3], v[152:155], v[184:187], v[0:3]
	v_mfma_f32_16x16x32_bf16 v[0:3], v[156:159], v[200:203], v[0:3]
	s_setprio 0
	s_barrier
; #define PG8_STAGE(bufoff, gbase, voff) do { _Pragma("unroll") for (int _i = 0; _i < 2; ++_i) \
;         __builtin_amdgcn_global_load_lds((const unsigned*)((const char*)(gbase) + (voff)[_i]), (PG8_LAS unsigned*)(lds + (bufoff) + ldsw + _i * 8192), 16, 0, 0); } while (0)
; #define PG8_LDA(dst, b, h) do { _Pragma("unroll") for (int m = 0; m < 4; ++m) _Pragma("unroll") for (int k = 0; k < 2; ++k) dst[m][k] = *(const PG8_LAS bf16x8*)(lds + PG8_SA(b, h) + aoff + m * 2048 + k * 1024); } while (0)
; #define PG8_LDB(dst, b, h) do { _Pragma("unroll") for (int n = 0; n < 2; ++n) _Pragma("unroll") for (int k = 0; k < 2; ++k) dst[n][k] = *(const PG8_LAS bf16x8*)(lds + PG8_SB(b, h) + boff + n * 2048 + k * 1024); } while (0)
; #define PG8_MMA(ai, bj, At, Bt) do { __builtin_amdgcn_s_setprio(1); _Pragma("unroll") for (int m = 0; m < 4; ++m) _Pragma("unroll") for (int n = 0; n < 2; ++n) _Pragma("unroll") for (int k = 0; k < 2; ++k) \
;         acc[ai][bj][m][n] = __builtin_amdgcn_mfma_f32_16x16x32_bf16(Bt[n][k], At[m][k], acc[ai][bj][m][n], 0, 0, 0); __builtin_amdgcn_s_setprio(0); } while (0)
; #define PG8_WAIT_V(n) asm volatile("s_waitcnt vmcnt(" #n ")" ::: "memory")
; #define PG8_WAIT_L(n) asm volatile("s_waitcnt lgkmcnt(" #n ")" ::: "memory")
; #define PG8_BAR __builtin_amdgcn_s_barrier()
; #define PG8_SCHED __builtin_amdgcn_sched_barrier(0)
; template <class Epi, class Sched, bool ALIGN_EPI = false, bool SP2 = false>
; __device__ __forceinline__ void gemm_phase(PG8_LAS unsigned char* lds, const Gemm g, const Sched& S, const Epi& E) {
;     ...
;             PG8_LDB(B0, 1, 0); PG8_LDB(B1, 1, 1); PG8_SCHED; PG8_LDA(At, 1, 0); PG8_STAGE(PG8_SA(0, 1), a2 + hstep, voffA);
;             PG8_WAIT_V(8); PG8_WAIT_L(0); PG8_BAR; PG8_MMA(0, 0, At, B0); PG8_MMA(0, 1, At, B1); PG8_BAR; PG8_SCHED;
	s_add_i32 s38, 0, 0x18000
	s_add_i32 s39, 0, 0x1c000
	ds_read_b128 v[80:83], v204 offset:32768
	ds_read_b128 v[88:91], v204 offset:33792
	ds_read_b128 v[104:107], v204 offset:34816
	ds_read_b128 v[108:111], v204 offset:35840
	ds_read_b128 v[128:131], v204 offset:49152
	ds_read_b128 v[132:135], v204 offset:50176
	ds_read_b128 v[152:155], v204 offset:51200
	ds_read_b128 v[156:159], v204 offset:52224
	s_add_u32 s36, s72, 0x80000
	s_addc_u32 s37, s73, 0
	s_mov_b32 m0, s77
	ds_read_b128 v[160:163], v240 offset:32768
	ds_read_b128 v[164:167], v240 offset:33792
	ds_read_b128 v[168:171], v240 offset:34816
	ds_read_b128 v[172:175], v240 offset:35840
	ds_read_b128 v[176:179], v240 offset:36864
	ds_read_b128 v[180:183], v240 offset:37888
	ds_read_b128 v[184:187], v240 offset:38912
	ds_read_b128 v[200:203], v240 offset:39936
	global_load_lds_dwordx4 v188, s[36:37]
	s_mov_b32 m0, s78
	s_nop 0
	global_load_lds_dwordx4 v194, s[36:37]
	s_waitcnt vmcnt(8)
	s_waitcnt lgkmcnt(0)
	s_barrier
	s_setprio 1
	s_waitcnt lgkmcnt(0)
	v_mfma_f32_16x16x32_bf16 v[148:151], v[80:83], v[160:163], v[148:151]
	v_mfma_f32_16x16x32_bf16 v[148:151], v[88:91], v[164:167], v[148:151]
	v_mfma_f32_16x16x32_bf16 v[144:147], v[104:107], v[160:163], v[144:147]
	v_mfma_f32_16x16x32_bf16 v[144:147], v[108:111], v[164:167], v[144:147]
	v_mfma_f32_16x16x32_bf16 v[124:127], v[80:83], v[168:171], v[124:127]
	v_mfma_f32_16x16x32_bf16 v[124:127], v[88:91], v[172:175], v[124:127]
	v_mfma_f32_16x16x32_bf16 v[120:123], v[104:107], v[168:171], v[120:123]
	v_mfma_f32_16x16x32_bf16 v[120:123], v[108:111], v[172:175], v[120:123]
	v_mfma_f32_16x16x32_bf16 v[100:103], v[80:83], v[176:179], v[100:103]
	v_mfma_f32_16x16x32_bf16 v[100:103], v[88:91], v[180:183], v[100:103]
	v_mfma_f32_16x16x32_bf16 v[96:99], v[104:107], v[176:179], v[96:99]
	v_mfma_f32_16x16x32_bf16 v[96:99], v[108:111], v[180:183], v[96:99]
	v_mfma_f32_16x16x32_bf16 v[76:79], v[80:83], v[184:187], v[76:79]
	v_mfma_f32_16x16x32_bf16 v[76:79], v[88:91], v[200:203], v[76:79]
	v_mfma_f32_16x16x32_bf16 v[72:75], v[104:107], v[184:187], v[72:75]
	v_mfma_f32_16x16x32_bf16 v[72:75], v[108:111], v[200:203], v[72:75]
	v_mfma_f32_16x16x32_bf16 v[140:143], v[128:131], v[160:163], v[140:143]
	v_mfma_f32_16x16x32_bf16 v[140:143], v[132:135], v[164:167], v[140:143]
	v_mfma_f32_16x16x32_bf16 v[136:139], v[152:155], v[160:163], v[136:139]
	v_mfma_f32_16x16x32_bf16 v[136:139], v[156:159], v[164:167], v[136:139]
	v_mfma_f32_16x16x32_bf16 v[116:119], v[128:131], v[168:171], v[116:119]
	v_mfma_f32_16x16x32_bf16 v[116:119], v[132:135], v[172:175], v[116:119]
	v_mfma_f32_16x16x32_bf16 v[112:115], v[152:155], v[168:171], v[112:115]
	v_mfma_f32_16x16x32_bf16 v[112:115], v[156:159], v[172:175], v[112:115]
	v_mfma_f32_16x16x32_bf16 v[92:95], v[128:131], v[176:179], v[92:95]
	v_mfma_f32_16x16x32_bf16 v[92:95], v[132:135], v[180:183], v[92:95]
	v_mfma_f32_16x16x32_bf16 v[84:87], v[152:155], v[176:179], v[84:87]
	v_mfma_f32_16x16x32_bf16 v[84:87], v[156:159], v[180:183], v[84:87]
	v_mfma_f32_16x16x32_bf16 v[68:71], v[128:131], v[184:187], v[68:71]
	v_mfma_f32_16x16x32_bf16 v[68:71], v[132:135], v[200:203], v[68:71]
	v_mfma_f32_16x16x32_bf16 v[64:67], v[152:155], v[184:187], v[64:67]
	v_mfma_f32_16x16x32_bf16 v[64:67], v[156:159], v[200:203], v[64:67]
	s_setprio 0
	s_barrier
	s_add_i32 s36, s38, s75
	s_mov_b32 m0, s36
	ds_read_b128 v[160:163], v240 offset:49152
	ds_read_b128 v[164:167], v240 offset:50176
	ds_read_b128 v[168:171], v240 offset:51200
	ds_read_b128 v[172:175], v240 offset:52224
	ds_read_b128 v[176:179], v240 offset:53248
	ds_read_b128 v[180:183], v240 offset:54272
	ds_read_b128 v[184:187], v240 offset:55296
	ds_read_b128 v[200:203], v240 offset:56320
	s_add_u32 s100, s70, 0x80
	s_addc_u32 s101, s71, 0
	global_load_lds_dwordx4 v188, s[100:101]
	s_add_i32 m0, s36, 0x2000
	s_add_u32 s36, s70, 0x80080
	s_addc_u32 s37, s71, 0
	s_add_i32 s38, s39, s75
	global_load_lds_dwordx4 v194, s[100:101]
	s_mov_b32 m0, s38
	s_nop 0
	global_load_lds_dwordx4 v188, s[36:37]
	s_add_i32 m0, s38, 0x2000
	s_nop 0
	global_load_lds_dwordx4 v194, s[36:37]
	s_mov_b32 m0, s79
	s_nop 0
	s_add_u32 s100, s72, 0x80
	s_addc_u32 s101, s73, 0
	global_load_lds_dwordx4 v188, s[100:101]
	s_mov_b32 m0, s80
	s_nop 0
	global_load_lds_dwordx4 v194, s[100:101]
	s_waitcnt vmcnt(8)
	s_waitcnt lgkmcnt(0)
	s_barrier
; #define PG8_WAIT_V(n) asm volatile("s_waitcnt vmcnt(" #n ")" ::: "memory")
;     __device__ __forceinline__ void operator()(const f32x4 (&acc)[2][2][4][2], const Unit& u, int wr, int wc, int fr, int fq) const {
;         const int r0 = u.pm * BM + wr * 64 + fr, c0 = u.pn * BM + 32 * wc + 8 * fq;
;         u32x4 hold[2][4][2];
; #pragma unroll
;         for (int ai = 0; ai < 2; ++ai)
; #pragma unroll
;             for (int m = 0; m < 4; ++m)
; #pragma unroll
; template <class Epi, class Sched, bool ALIGN_EPI = false, bool SP2 = false>
; __device__ __forceinline__ void gemm_phase(PG8_LAS unsigned char* lds, const Gemm g, const Sched& S, const Epi& E) {
;     ...
;             PG8_WAIT_V(8); PG8_WAIT_L(0); PG8_BAR; PG8_MMA(0, 0, At, B0); PG8_MMA(0, 1, At, B1); PG8_BAR; PG8_SCHED;
;             PG8_LDA(At, 1, 1); PG8_STAGE(PG8_SB(1, 0), b3, voffB); PG8_STAGE(PG8_SB(1, 1), b3 + hstep, voffB); PG8_STAGE(PG8_SA(1, 0), a3, voffA);
;             PG8_WAIT_V(8); PG8_WAIT_L(0); PG8_BAR; PG8_MMA(1, 0, At, B0); PG8_MMA(1, 1, At, B1); PG8_BAR; PG8_SCHED;
;             } else {
;             PG8_LDB(B0, 0, 0); PG8_SCHED; PG8_LDA(At, 0, 0); PG8_STAGE(PG8_SA(1, 1), a1 + hstep, voffA);
;             PG8_WAIT_L(8); PG8_BAR; PG8_WAIT_L(0); PG8_MMA(0, 0, At, B0); PG8_BAR; PG8_SCHED;
;             PG8_LDB(B1, 0, 1); PG8_STAGE(PG8_SB(0, 0), b2, voffB);
;             PG8_BAR; PG8_WAIT_L(0); PG8_MMA(0, 1, At, B1); PG8_BAR;
;             PG8_LDA(At, 0, 1); PG8_STAGE(PG8_SA(0, 0), a2, voffA);
;             PG8_BAR; PG8_WAIT_L(0); PG8_MMA(1, 0, At, B0); PG8_BAR; PG8_SCHED;
;             PG8_STAGE(PG8_SB(0, 1), b2 + hstep, voffB);
;             PG8_WAIT_V(6); PG8_BAR; PG8_MMA(1, 1, At, B1); PG8_BAR;
;             PG8_LDB(B0, 1, 0); PG8_SCHED; PG8_LDA(At, 1, 0); PG8_STAGE(PG8_SA(0, 1), a2 + hstep, voffA);
;             PG8_WAIT_L(8); PG8_BAR; PG8_WAIT_L(0); PG8_MMA(0, 0, At, B0); PG8_BAR; PG8_SCHED;
;             PG8_LDB(B1, 1, 1); PG8_STAGE(PG8_SB(1, 0), b3, voffB);
;             PG8_BAR; PG8_WAIT_L(0); PG8_MMA(0, 1, At, B1); PG8_BAR;
;             PG8_LDA(At, 1, 1); PG8_STAGE(PG8_SA(1, 0), a3, voffA);
;             PG8_BAR; PG8_WAIT_L(0); PG8_MMA(1, 0, At, B0); PG8_BAR; PG8_SCHED;
;             PG8_STAGE(PG8_SB(1, 1), b3 + hstep, voffB);
;             PG8_WAIT_V(6); PG8_BAR; PG8_MMA(1, 1, At, B1); PG8_BAR;
;             }
;         }
;         if constexpr (ALIGN_EPI) { if (wr == 0) PG8_BAR; }
	s_setprio 1
	s_waitcnt lgkmcnt(0)
	v_mfma_f32_16x16x32_bf16 v[60:63], v[80:83], v[160:163], v[60:63]
	v_mfma_f32_16x16x32_bf16 v[60:63], v[88:91], v[164:167], v[60:63]
	v_mfma_f32_16x16x32_bf16 v[56:59], v[104:107], v[160:163], v[56:59]
	v_mfma_f32_16x16x32_bf16 v[56:59], v[108:111], v[164:167], v[56:59]
	v_mfma_f32_16x16x32_bf16 v[44:47], v[80:83], v[168:171], v[44:47]
	v_mfma_f32_16x16x32_bf16 v[44:47], v[88:91], v[172:175], v[44:47]
	v_mfma_f32_16x16x32_bf16 v[40:43], v[104:107], v[168:171], v[40:43]
	v_mfma_f32_16x16x32_bf16 v[40:43], v[108:111], v[172:175], v[40:43]
	v_mfma_f32_16x16x32_bf16 v[28:31], v[80:83], v[176:179], v[28:31]
	v_mfma_f32_16x16x32_bf16 v[28:31], v[88:91], v[180:183], v[28:31]
	v_mfma_f32_16x16x32_bf16 v[24:27], v[104:107], v[176:179], v[24:27]
	v_mfma_f32_16x16x32_bf16 v[24:27], v[108:111], v[180:183], v[24:27]
	v_mfma_f32_16x16x32_bf16 v[12:15], v[80:83], v[184:187], v[12:15]
	v_mfma_f32_16x16x32_bf16 v[12:15], v[88:91], v[200:203], v[12:15]
	v_mfma_f32_16x16x32_bf16 v[8:11], v[104:107], v[184:187], v[8:11]
	v_mfma_f32_16x16x32_bf16 v[8:11], v[108:111], v[200:203], v[8:11]
	v_mfma_f32_16x16x32_bf16 v[52:55], v[128:131], v[160:163], v[52:55]
	v_mfma_f32_16x16x32_bf16 v[52:55], v[132:135], v[164:167], v[52:55]
	v_mfma_f32_16x16x32_bf16 v[48:51], v[152:155], v[160:163], v[48:51]
	v_mfma_f32_16x16x32_bf16 v[48:51], v[156:159], v[164:167], v[48:51]
	v_mfma_f32_16x16x32_bf16 v[36:39], v[128:131], v[168:171], v[36:39]
	v_mfma_f32_16x16x32_bf16 v[36:39], v[132:135], v[172:175], v[36:39]
	v_mfma_f32_16x16x32_bf16 v[32:35], v[152:155], v[168:171], v[32:35]
	v_mfma_f32_16x16x32_bf16 v[32:35], v[156:159], v[172:175], v[32:35]
	v_mfma_f32_16x16x32_bf16 v[20:23], v[128:131], v[176:179], v[20:23]
	v_mfma_f32_16x16x32_bf16 v[20:23], v[132:135], v[180:183], v[20:23]
	v_mfma_f32_16x16x32_bf16 v[16:19], v[152:155], v[176:179], v[16:19]
	v_mfma_f32_16x16x32_bf16 v[16:19], v[156:159], v[180:183], v[16:19]
	v_mfma_f32_16x16x32_bf16 v[4:7], v[128:131], v[184:187], v[4:7]
	v_mfma_f32_16x16x32_bf16 v[4:7], v[132:135], v[200:203], v[4:7]
	v_mfma_f32_16x16x32_bf16 v[0:3], v[152:155], v[184:187], v[0:3]
	v_mfma_f32_16x16x32_bf16 v[0:3], v[156:159], v[200:203], v[0:3]
	s_setprio 0
	s_barrier
	s_add_i32 s89, s89, 2
	s_add_u32 s68, s68, 0x100
	s_addc_u32 s69, s69, 0
	s_add_u32 s3, s3, 0x100
	s_addc_u32 s88, s88, 0
	s_cmp_gt_u32 s89, 29
	s_cbranch_scc0 .LBB0_205
	v_lshl_add_u32 v202, s66, 8, v237
	v_lshl_or_b32 v200, s8, 8, v239
	v_ashrrev_i32_e32 v201, 31, v200
	v_ashrrev_i32_e32 v203, 31, v202
	v_or_b32_e32 v222, 16, v202
	v_lshl_add_u64 v[80:81], v[200:201], 1, s[34:35]
	v_lshlrev_b64 v[242:243], 12, v[202:203]
	v_ashrrev_i32_e32 v223, 31, v222
	v_or_b32_e32 v218, 32, v202
	v_lshl_add_u64 v[82:83], v[80:81], 0, v[242:243]
	v_lshlrev_b64 v[220:221], 12, v[222:223]
	v_ashrrev_i32_e32 v219, 31, v218
	v_or_b32_e32 v214, 48, v202
	global_load_dwordx4 v[228:231], v[82:83], off
	global_load_dwordx4 v[184:187], v[82:83], off offset:256
	v_lshl_add_u64 v[82:83], v[80:81], 0, v[220:221]
	v_lshlrev_b64 v[216:217], 12, v[218:219]
	v_ashrrev_i32_e32 v215, 31, v214
	s_mov_b64 s[8:9], 0x80000
	global_load_dwordx4 v[180:183], v[82:83], off
	global_load_dwordx4 v[176:179], v[82:83], off offset:256
	v_lshl_add_u64 v[82:83], v[80:81], 0, v[216:217]
	v_lshlrev_b64 v[212:213], 12, v[214:215]
	v_lshl_add_u64 v[210:211], v[242:243], 0, s[8:9]
	s_mov_b64 s[8:9], 0x90000
	global_load_dwordx4 v[172:175], v[82:83], off
	global_load_dwordx4 v[168:171], v[82:83], off offset:256
	v_lshl_add_u64 v[82:83], v[80:81], 0, v[212:213]
	v_lshl_add_u64 v[208:209], v[242:243], 0, s[8:9]
	s_mov_b64 s[8:9], 0xa0000
	global_load_dwordx4 v[164:167], v[82:83], off
	global_load_dwordx4 v[160:163], v[82:83], off offset:256
	v_lshl_add_u64 v[82:83], v[80:81], 0, v[210:211]
	v_lshl_add_u64 v[206:207], v[242:243], 0, s[8:9]
	s_mov_b64 s[8:9], 0xb0000
	global_load_dwordx4 v[156:159], v[82:83], off
	global_load_dwordx4 v[152:155], v[82:83], off offset:256
	v_lshl_add_u64 v[82:83], v[80:81], 0, v[208:209]
	v_lshl_add_u64 v[204:205], v[242:243], 0, s[8:9]
	global_load_dwordx4 v[132:135], v[82:83], off
	global_load_dwordx4 v[128:131], v[82:83], off offset:256
	v_lshl_add_u64 v[82:83], v[80:81], 0, v[206:207]
	v_lshl_add_u64 v[80:81], v[80:81], 0, v[204:205]
	global_load_dwordx4 v[108:111], v[82:83], off
	global_load_dwordx4 v[104:107], v[82:83], off offset:256
	global_load_dwordx4 v[88:91], v[80:81], off
	s_nop 0
	global_load_dwordx4 v[80:83], v[80:81], off offset:256
	v_lshl_add_u64 v[242:243], s[34:35], 0, v[242:243]
	s_and_b64 vcc, exec, s[56:57]
	s_cbranch_vccz .LBB0_208
	s_barrier

; #define PG8_STAGE(bufoff, gbase, voff) do { _Pragma("unroll") for (int _i = 0; _i < 2; ++_i) \
;         __builtin_amdgcn_global_load_lds((const unsigned*)((const char*)(gbase) + (voff)[_i]), (PG8_LAS unsigned*)(lds + (bufoff) + ldsw + _i * 8192), 16, 0, 0); } while (0)
; #define PG8_LDA(dst, b, h) do { _Pragma("unroll") for (int m = 0; m < 4; ++m) _Pragma("unroll") for (int k = 0; k < 2; ++k) dst[m][k] = *(const PG8_LAS bf16x8*)(lds + PG8_SA(b, h) + aoff + m * 2048 + k * 1024); } while (0)
; #define PG8_LDB(dst, b, h) do { _Pragma("unroll") for (int n = 0; n < 2; ++n) _Pragma("unroll") for (int k = 0; k < 2; ++k) dst[n][k] = *(const PG8_LAS bf16x8*)(lds + PG8_SB(b, h) + boff + n * 2048 + k * 1024); } while (0)
; #define PG8_WAIT_V(n) asm volatile("s_waitcnt vmcnt(" #n ")" ::: "memory")
; #define PG8_WAIT_L(n) asm volatile("s_waitcnt lgkmcnt(" #n ")" ::: "memory")
; #define PG8_BAR __builtin_amdgcn_s_barrier()
; #define PG8_SCHED __builtin_amdgcn_sched_barrier(0)
; template <class Epi, class Sched, bool ALIGN_EPI = false, bool SP2 = false>
; __device__ __forceinline__ void gemm_phase(PG8_LAS unsigned char* lds, const Gemm g, const Sched& S, const Epi& E) {
;     ...
;         const char* nA = has_next ? (const char*)g.A + (size_t)nxt.pm * tstep : cA; const char* nB = has_next ? (const char*)g.Bt + (size_t)nxt.pn * tstep : cB;
;         for (int t = 0; t < nt; t += 2) {
;             const bool last = (t == nt - 2);
;             const char* a1 = cA + (size_t)(t + 1) * kstep;
;             const char* a2 = last ? nA : cA + (size_t)(t + 2) * kstep; const char* b2 = last ? nB : cB + (size_t)(t + 2) * kstep;
;             const char* a3 = a2 + kstep; const char* b3 = b2 + kstep;
;             if (last && has_next) S.a_ready(nxt);
;             if constexpr (SP2) {
;             PG8_LDB(B0, 0, 0); PG8_LDB(B1, 0, 1); PG8_SCHED; PG8_LDA(At, 0, 0); PG8_STAGE(PG8_SA(1, 1), a1 + hstep, voffA);
;             PG8_WAIT_V(8); PG8_WAIT_L(0); PG8_BAR; PG8_MMA(0, 0, At, B0); PG8_MMA(0, 1, At, B1); PG8_BAR; PG8_SCHED;
;             PG8_LDA(At, 0, 1); PG8_STAGE(PG8_SB(0, 0), b2, voffB); PG8_STAGE(PG8_SB(0, 1), b2 + hstep, voffB); PG8_STAGE(PG8_SA(0, 0), a2, voffA);
;             PG8_WAIT_V(8); PG8_WAIT_L(0); PG8_BAR; PG8_MMA(1, 0, At, B0); PG8_MMA(1, 1, At, B1); PG8_BAR; PG8_SCHED;
.LBB0_297:
	s_ashr_i32 s67, s66, 31
	s_lshl_b64 s[76:77], s[66:67], 20
	s_add_u32 s78, s34, s76
	s_addc_u32 s79, s35, s77
	s_and_b64 s[76:77], s[12:13], exec
	s_cselect_b32 s65, s79, s69
	s_cselect_b32 s67, s78, s68
	s_ashr_i32 s75, s74, 31
	s_lshl_b64 s[76:77], s[74:75], 20
	s_add_u32 s76, s0, s76
	s_addc_u32 s77, s1, s77
	s_and_b64 s[94:95], s[12:13], exec
	s_cselect_b32 s73, s77, s71
	s_cselect_b32 s75, s76, s70
	s_add_u32 vcc_lo, s68, 0x80080
	s_addc_u32 vcc_hi, s69, 0
	s_add_u32 s3, s70, 0x100
	s_addc_u32 s94, s71, 0
	s_mov_b32 s95, -2
	s_add_u32 s36, vcc_lo, 0xfff80080
	s_addc_u32 s37, vcc_hi, -1
	s_add_i32 s38, 0, 0x10000
	s_cmp_eq_u32 s95, 28
	s_cselect_b32 s71, s65, s37
	s_cselect_b32 s70, s67, s36
	s_cselect_b32 s69, s73, s94
	s_cselect_b32 s68, s75, s3
	s_add_i32 s39, 0, 0x14000
	s_add_i32 m0, s88, 0xc000
	global_load_lds_dwordx4 v142, vcc
	s_add_i32 m0, s88, 0xe000
	s_nop 0
	global_load_lds_dwordx4 v144, vcc
	s_waitcnt vmcnt(24)
	s_waitcnt lgkmcnt(0)
	s_barrier
	s_setprio 1
	s_waitcnt lgkmcnt(0)
	v_mfma_f32_16x16x32_bf16 v[136:139], v[64:67], v[174:177], 0
	v_mfma_f32_16x16x32_bf16 v[136:139], v[68:71], v[178:181], v[136:139]
	v_mfma_f32_16x16x32_bf16 v[132:135], v[72:75], v[174:177], 0
	v_mfma_f32_16x16x32_bf16 v[132:135], v[146:149], v[178:181], v[132:135]
	v_mfma_f32_16x16x32_bf16 v[120:123], v[64:67], v[182:185], 0
	v_mfma_f32_16x16x32_bf16 v[120:123], v[68:71], v[194:197], v[120:123]
	v_mfma_f32_16x16x32_bf16 v[116:119], v[72:75], v[182:185], 0
	v_mfma_f32_16x16x32_bf16 v[116:119], v[146:149], v[194:197], v[116:119]
	v_mfma_f32_16x16x32_bf16 v[104:107], v[64:67], v[198:201], 0
	v_mfma_f32_16x16x32_bf16 v[104:107], v[68:71], v[202:205], v[104:107]
	v_mfma_f32_16x16x32_bf16 v[100:103], v[72:75], v[198:201], 0
	v_mfma_f32_16x16x32_bf16 v[100:103], v[146:149], v[202:205], v[100:103]
	v_mfma_f32_16x16x32_bf16 v[88:91], v[64:67], v[206:209], 0
	v_mfma_f32_16x16x32_bf16 v[88:91], v[68:71], v[210:213], v[88:91]
	v_mfma_f32_16x16x32_bf16 v[84:87], v[72:75], v[206:209], 0
	v_mfma_f32_16x16x32_bf16 v[84:87], v[146:149], v[210:213], v[84:87]
	v_mfma_f32_16x16x32_bf16 v[128:131], v[150:153], v[174:177], 0
	v_mfma_f32_16x16x32_bf16 v[128:131], v[154:157], v[178:181], v[128:131]
	v_mfma_f32_16x16x32_bf16 v[124:127], v[158:161], v[174:177], 0
	v_mfma_f32_16x16x32_bf16 v[124:127], v[170:173], v[178:181], v[124:127]
	v_mfma_f32_16x16x32_bf16 v[112:115], v[150:153], v[182:185], 0
	v_mfma_f32_16x16x32_bf16 v[112:115], v[154:157], v[194:197], v[112:115]
	v_mfma_f32_16x16x32_bf16 v[108:111], v[158:161], v[182:185], 0
	v_mfma_f32_16x16x32_bf16 v[108:111], v[170:173], v[194:197], v[108:111]
	v_mfma_f32_16x16x32_bf16 v[96:99], v[150:153], v[198:201], 0
	v_mfma_f32_16x16x32_bf16 v[96:99], v[154:157], v[202:205], v[96:99]
	v_mfma_f32_16x16x32_bf16 v[92:95], v[158:161], v[198:201], 0
	v_mfma_f32_16x16x32_bf16 v[92:95], v[170:173], v[202:205], v[92:95]
	v_mfma_f32_16x16x32_bf16 v[80:83], v[150:153], v[206:209], 0
	v_mfma_f32_16x16x32_bf16 v[80:83], v[154:157], v[210:213], v[80:83]
	v_mfma_f32_16x16x32_bf16 v[76:79], v[158:161], v[206:209], 0
	v_mfma_f32_16x16x32_bf16 v[76:79], v[170:173], v[210:213], v[76:79]
	s_setprio 0
	s_barrier
	s_add_i32 s36, s38, s87
	s_mov_b32 m0, s36
	ds_read_b128 v[174:177], v169 offset:16384
	ds_read_b128 v[178:181], v169 offset:17408
	ds_read_b128 v[182:185], v169 offset:18432
	ds_read_b128 v[194:197], v169 offset:19456
	ds_read_b128 v[198:201], v169 offset:20480
	ds_read_b128 v[202:205], v169 offset:21504
	ds_read_b128 v[206:209], v169 offset:22528
	ds_read_b128 v[210:213], v169 offset:23552
	global_load_lds_dwordx4 v188, s[68:69]
	s_add_i32 m0, s36, 0x2000
	s_add_u32 s36, s68, 0x80000
	s_addc_u32 s37, s69, 0
	s_add_i32 s38, s39, s87
	global_load_lds_dwordx4 v140, s[68:69]
	s_mov_b32 m0, s38
	s_nop 0
	global_load_lds_dwordx4 v188, s[36:37]
	s_add_i32 m0, s38, 0x2000
	s_nop 0
	global_load_lds_dwordx4 v140, s[36:37]
	s_mov_b32 m0, s88
	s_nop 0
	global_load_lds_dwordx4 v188, s[70:71]
	s_mov_b32 m0, s89
	s_nop 0
	global_load_lds_dwordx4 v140, s[70:71]
	s_waitcnt vmcnt(24)
	s_waitcnt lgkmcnt(0)
	s_barrier
	s_setprio 1
	s_waitcnt lgkmcnt(0)
	v_mfma_f32_16x16x32_bf16 v[56:59], v[64:67], v[174:177], 0
	v_mfma_f32_16x16x32_bf16 v[56:59], v[68:71], v[178:181], v[56:59]
	v_mfma_f32_16x16x32_bf16 v[60:63], v[72:75], v[174:177], 0
	v_mfma_f32_16x16x32_bf16 v[60:63], v[146:149], v[178:181], v[60:63]
	v_mfma_f32_16x16x32_bf16 v[40:43], v[64:67], v[182:185], 0
	v_mfma_f32_16x16x32_bf16 v[40:43], v[68:71], v[194:197], v[40:43]
	v_mfma_f32_16x16x32_bf16 v[44:47], v[72:75], v[182:185], 0
	v_mfma_f32_16x16x32_bf16 v[44:47], v[146:149], v[194:197], v[44:47]
	v_mfma_f32_16x16x32_bf16 v[24:27], v[64:67], v[198:201], 0
	v_mfma_f32_16x16x32_bf16 v[24:27], v[68:71], v[202:205], v[24:27]
	v_mfma_f32_16x16x32_bf16 v[28:31], v[72:75], v[198:201], 0
	v_mfma_f32_16x16x32_bf16 v[28:31], v[146:149], v[202:205], v[28:31]
	v_mfma_f32_16x16x32_bf16 v[8:11], v[64:67], v[206:209], 0
	v_mfma_f32_16x16x32_bf16 v[8:11], v[68:71], v[210:213], v[8:11]
	v_mfma_f32_16x16x32_bf16 v[12:15], v[72:75], v[206:209], 0
	v_mfma_f32_16x16x32_bf16 v[12:15], v[146:149], v[210:213], v[12:15]
	v_mfma_f32_16x16x32_bf16 v[52:55], v[150:153], v[174:177], 0
	v_mfma_f32_16x16x32_bf16 v[52:55], v[154:157], v[178:181], v[52:55]
	v_mfma_f32_16x16x32_bf16 v[48:51], v[158:161], v[174:177], 0
	v_mfma_f32_16x16x32_bf16 v[48:51], v[170:173], v[178:181], v[48:51]
	v_mfma_f32_16x16x32_bf16 v[36:39], v[150:153], v[182:185], 0
	v_mfma_f32_16x16x32_bf16 v[36:39], v[154:157], v[194:197], v[36:39]
	v_mfma_f32_16x16x32_bf16 v[32:35], v[158:161], v[182:185], 0
	v_mfma_f32_16x16x32_bf16 v[32:35], v[170:173], v[194:197], v[32:35]
	v_mfma_f32_16x16x32_bf16 v[20:23], v[150:153], v[198:201], 0
	v_mfma_f32_16x16x32_bf16 v[20:23], v[154:157], v[202:205], v[20:23]
	v_mfma_f32_16x16x32_bf16 v[16:19], v[158:161], v[198:201], 0
	v_mfma_f32_16x16x32_bf16 v[16:19], v[170:173], v[202:205], v[16:19]
	v_mfma_f32_16x16x32_bf16 v[4:7], v[150:153], v[206:209], 0
	v_mfma_f32_16x16x32_bf16 v[4:7], v[154:157], v[210:213], v[4:7]
	v_mfma_f32_16x16x32_bf16 v[0:3], v[158:161], v[206:209], 0
	v_mfma_f32_16x16x32_bf16 v[0:3], v[170:173], v[210:213], v[0:3]
	s_setprio 0
	s_barrier
; #define PG8_STAGE(bufoff, gbase, voff) do { _Pragma("unroll") for (int _i = 0; _i < 2; ++_i) \
;         __builtin_amdgcn_global_load_lds((const unsigned*)((const char*)(gbase) + (voff)[_i]), (PG8_LAS unsigned*)(lds + (bufoff) + ldsw + _i * 8192), 16, 0, 0); } while (0)
; #define PG8_LDA(dst, b, h) do { _Pragma("unroll") for (int m = 0; m < 4; ++m) _Pragma("unroll") for (int k = 0; k < 2; ++k) dst[m][k] = *(const PG8_LAS bf16x8*)(lds + PG8_SA(b, h) + aoff + m * 2048 + k * 1024); } while (0)
; #define PG8_LDB(dst, b, h) do { _Pragma("unroll") for (int n = 0; n < 2; ++n) _Pragma("unroll") for (int k = 0; k < 2; ++k) dst[n][k] = *(const PG8_LAS bf16x8*)(lds + PG8_SB(b, h) + boff + n * 2048 + k * 1024); } while (0)
; #define PG8_MMA(ai, bj, At, Bt) do { __builtin_amdgcn_s_setprio(1); _Pragma("unroll") for (int m = 0; m < 4; ++m) _Pragma("unroll") for (int n = 0; n < 2; ++n) _Pragma("unroll") for (int k = 0; k < 2; ++k) \
;         acc[ai][bj][m][n] = __builtin_amdgcn_mfma_f32_16x16x32_bf16(Bt[n][k], At[m][k], acc[ai][bj][m][n], 0, 0, 0); __builtin_amdgcn_s_setprio(0); } while (0)
; #define PG8_WAIT_V(n) asm volatile("s_waitcnt vmcnt(" #n ")" ::: "memory")
; #define PG8_WAIT_L(n) asm volatile("s_waitcnt lgkmcnt(" #n ")" ::: "memory")
; #define PG8_BAR __builtin_amdgcn_s_barrier()
; #define PG8_SCHED __builtin_amdgcn_sched_barrier(0)
; template <class Epi, class Sched, bool ALIGN_EPI = false, bool SP2 = false>
; __device__ __forceinline__ void gemm_phase(PG8_LAS unsigned char* lds, const Gemm g, const Sched& S, const Epi& E) {
;     ...
;             PG8_LDB(B0, 1, 0); PG8_LDB(B1, 1, 1); PG8_SCHED; PG8_LDA(At, 1, 0); PG8_STAGE(PG8_SA(0, 1), a2 + hstep, voffA);
;             PG8_WAIT_V(8); PG8_WAIT_L(0); PG8_BAR; PG8_MMA(0, 0, At, B0); PG8_MMA(0, 1, At, B1); PG8_BAR; PG8_SCHED;
;             PG8_LDA(At, 1, 1); PG8_STAGE(PG8_SB(1, 0), b3, voffB); PG8_STAGE(PG8_SB(1, 1), b3 + hstep, voffB); PG8_STAGE(PG8_SA(1, 0), a3, voffA);
;             PG8_WAIT_V(8); PG8_WAIT_L(0); PG8_BAR; PG8_MMA(1, 0, At, B0); PG8_MMA(1, 1, At, B1); PG8_BAR; PG8_SCHED;
	s_add_i32 s38, 0, 0x18000
	s_add_i32 s39, 0, 0x1c000
	ds_read_b128 v[64:67], v214 offset:32768
	ds_read_b128 v[68:71], v214 offset:33792
	ds_read_b128 v[72:75], v214 offset:34816
	ds_read_b128 v[146:149], v214 offset:35840
	ds_read_b128 v[150:153], v214 offset:49152
	ds_read_b128 v[154:157], v214 offset:50176
	ds_read_b128 v[158:161], v214 offset:51200
	ds_read_b128 v[170:173], v214 offset:52224
	s_add_u32 s36, s70, 0x80000
	s_addc_u32 s37, s71, 0
	s_mov_b32 m0, s14
	ds_read_b128 v[174:177], v169 offset:32768
	ds_read_b128 v[178:181], v169 offset:33792
	ds_read_b128 v[182:185], v169 offset:34816
	ds_read_b128 v[194:197], v169 offset:35840
	ds_read_b128 v[198:201], v169 offset:36864
	ds_read_b128 v[202:205], v169 offset:37888
	ds_read_b128 v[206:209], v169 offset:38912
	ds_read_b128 v[210:213], v169 offset:39936
	global_load_lds_dwordx4 v188, s[36:37]
	s_mov_b32 m0, s15
	s_nop 0
	global_load_lds_dwordx4 v140, s[36:37]
	s_waitcnt vmcnt(8)
	s_waitcnt lgkmcnt(0)
	s_barrier
	s_setprio 1
	s_waitcnt lgkmcnt(0)
	v_mfma_f32_16x16x32_bf16 v[136:139], v[64:67], v[174:177], v[136:139]
	v_mfma_f32_16x16x32_bf16 v[136:139], v[68:71], v[178:181], v[136:139]
	v_mfma_f32_16x16x32_bf16 v[132:135], v[72:75], v[174:177], v[132:135]
	v_mfma_f32_16x16x32_bf16 v[132:135], v[146:149], v[178:181], v[132:135]
	v_mfma_f32_16x16x32_bf16 v[120:123], v[64:67], v[182:185], v[120:123]
	v_mfma_f32_16x16x32_bf16 v[120:123], v[68:71], v[194:197], v[120:123]
	v_mfma_f32_16x16x32_bf16 v[116:119], v[72:75], v[182:185], v[116:119]
	v_mfma_f32_16x16x32_bf16 v[116:119], v[146:149], v[194:197], v[116:119]
	v_mfma_f32_16x16x32_bf16 v[104:107], v[64:67], v[198:201], v[104:107]
	v_mfma_f32_16x16x32_bf16 v[104:107], v[68:71], v[202:205], v[104:107]
	v_mfma_f32_16x16x32_bf16 v[100:103], v[72:75], v[198:201], v[100:103]
	v_mfma_f32_16x16x32_bf16 v[100:103], v[146:149], v[202:205], v[100:103]
	v_mfma_f32_16x16x32_bf16 v[88:91], v[64:67], v[206:209], v[88:91]
	v_mfma_f32_16x16x32_bf16 v[88:91], v[68:71], v[210:213], v[88:91]
	v_mfma_f32_16x16x32_bf16 v[84:87], v[72:75], v[206:209], v[84:87]
	v_mfma_f32_16x16x32_bf16 v[84:87], v[146:149], v[210:213], v[84:87]
	v_mfma_f32_16x16x32_bf16 v[128:131], v[150:153], v[174:177], v[128:131]
	v_mfma_f32_16x16x32_bf16 v[128:131], v[154:157], v[178:181], v[128:131]
	v_mfma_f32_16x16x32_bf16 v[124:127], v[158:161], v[174:177], v[124:127]
	v_mfma_f32_16x16x32_bf16 v[124:127], v[170:173], v[178:181], v[124:127]
	v_mfma_f32_16x16x32_bf16 v[112:115], v[150:153], v[182:185], v[112:115]
	v_mfma_f32_16x16x32_bf16 v[112:115], v[154:157], v[194:197], v[112:115]
	v_mfma_f32_16x16x32_bf16 v[108:111], v[158:161], v[182:185], v[108:111]
	v_mfma_f32_16x16x32_bf16 v[108:111], v[170:173], v[194:197], v[108:111]
	v_mfma_f32_16x16x32_bf16 v[96:99], v[150:153], v[198:201], v[96:99]
	v_mfma_f32_16x16x32_bf16 v[96:99], v[154:157], v[202:205], v[96:99]
	v_mfma_f32_16x16x32_bf16 v[92:95], v[158:161], v[198:201], v[92:95]
	v_mfma_f32_16x16x32_bf16 v[92:95], v[170:173], v[202:205], v[92:95]
	v_mfma_f32_16x16x32_bf16 v[80:83], v[150:153], v[206:209], v[80:83]
	v_mfma_f32_16x16x32_bf16 v[80:83], v[154:157], v[210:213], v[80:83]
	v_mfma_f32_16x16x32_bf16 v[76:79], v[158:161], v[206:209], v[76:79]
	v_mfma_f32_16x16x32_bf16 v[76:79], v[170:173], v[210:213], v[76:79]
	s_setprio 0
	s_barrier
	s_add_i32 s36, s38, s87
	s_mov_b32 m0, s36
	ds_read_b128 v[174:177], v169 offset:49152
	ds_read_b128 v[178:181], v169 offset:50176
	ds_read_b128 v[182:185], v169 offset:51200
	ds_read_b128 v[194:197], v169 offset:52224
	ds_read_b128 v[198:201], v169 offset:53248
	ds_read_b128 v[202:205], v169 offset:54272
	ds_read_b128 v[206:209], v169 offset:55296
	ds_read_b128 v[210:213], v169 offset:56320
	s_add_u32 s100, s68, 0x80
	s_addc_u32 s101, s69, 0
	global_load_lds_dwordx4 v188, s[100:101]
	s_add_i32 m0, s36, 0x2000
	s_add_u32 s36, s68, 0x80080
	s_addc_u32 s37, s69, 0
	s_add_i32 s38, s39, s87
	global_load_lds_dwordx4 v140, s[100:101]
	s_mov_b32 m0, s38
	s_nop 0
	global_load_lds_dwordx4 v188, s[36:37]
	s_add_i32 m0, s38, 0x2000
	s_nop 0
	global_load_lds_dwordx4 v140, s[36:37]
	s_mov_b32 m0, s81
	s_nop 0
	s_add_u32 s100, s70, 0x80
	s_addc_u32 s101, s71, 0
	global_load_lds_dwordx4 v188, s[100:101]
	s_mov_b32 m0, s80
	s_nop 0
	global_load_lds_dwordx4 v140, s[100:101]
	s_waitcnt vmcnt(8)
	s_waitcnt lgkmcnt(0)
	s_barrier
	s_setprio 1
	s_waitcnt lgkmcnt(0)
	v_mfma_f32_16x16x32_bf16 v[56:59], v[64:67], v[174:177], v[56:59]
	v_mfma_f32_16x16x32_bf16 v[56:59], v[68:71], v[178:181], v[56:59]
	v_mfma_f32_16x16x32_bf16 v[60:63], v[72:75], v[174:177], v[60:63]
	v_mfma_f32_16x16x32_bf16 v[60:63], v[146:149], v[178:181], v[60:63]
	v_mfma_f32_16x16x32_bf16 v[40:43], v[64:67], v[182:185], v[40:43]
	v_mfma_f32_16x16x32_bf16 v[40:43], v[68:71], v[194:197], v[40:43]
	v_mfma_f32_16x16x32_bf16 v[44:47], v[72:75], v[182:185], v[44:47]
	v_mfma_f32_16x16x32_bf16 v[44:47], v[146:149], v[194:197], v[44:47]
	v_mfma_f32_16x16x32_bf16 v[24:27], v[64:67], v[198:201], v[24:27]
	v_mfma_f32_16x16x32_bf16 v[24:27], v[68:71], v[202:205], v[24:27]
	v_mfma_f32_16x16x32_bf16 v[28:31], v[72:75], v[198:201], v[28:31]
	v_mfma_f32_16x16x32_bf16 v[28:31], v[146:149], v[202:205], v[28:31]
	v_mfma_f32_16x16x32_bf16 v[8:11], v[64:67], v[206:209], v[8:11]
	v_mfma_f32_16x16x32_bf16 v[8:11], v[68:71], v[210:213], v[8:11]
	v_mfma_f32_16x16x32_bf16 v[12:15], v[72:75], v[206:209], v[12:15]
	v_mfma_f32_16x16x32_bf16 v[12:15], v[146:149], v[210:213], v[12:15]
	v_mfma_f32_16x16x32_bf16 v[52:55], v[150:153], v[174:177], v[52:55]
	v_mfma_f32_16x16x32_bf16 v[52:55], v[154:157], v[178:181], v[52:55]
	v_mfma_f32_16x16x32_bf16 v[48:51], v[158:161], v[174:177], v[48:51]
	v_mfma_f32_16x16x32_bf16 v[48:51], v[170:173], v[178:181], v[48:51]
	v_mfma_f32_16x16x32_bf16 v[36:39], v[150:153], v[182:185], v[36:39]
	v_mfma_f32_16x16x32_bf16 v[36:39], v[154:157], v[194:197], v[36:39]
	v_mfma_f32_16x16x32_bf16 v[32:35], v[158:161], v[182:185], v[32:35]
	v_mfma_f32_16x16x32_bf16 v[32:35], v[170:173], v[194:197], v[32:35]
	v_mfma_f32_16x16x32_bf16 v[20:23], v[150:153], v[198:201], v[20:23]
	v_mfma_f32_16x16x32_bf16 v[20:23], v[154:157], v[202:205], v[20:23]
	v_mfma_f32_16x16x32_bf16 v[16:19], v[158:161], v[198:201], v[16:19]
	v_mfma_f32_16x16x32_bf16 v[16:19], v[170:173], v[202:205], v[16:19]
	v_mfma_f32_16x16x32_bf16 v[4:7], v[150:153], v[206:209], v[4:7]
	v_mfma_f32_16x16x32_bf16 v[4:7], v[154:157], v[210:213], v[4:7]
	v_mfma_f32_16x16x32_bf16 v[0:3], v[158:161], v[206:209], v[0:3]
	v_mfma_f32_16x16x32_bf16 v[0:3], v[170:173], v[210:213], v[0:3]
	s_setprio 0
	s_barrier
	s_add_i32 s95, s95, 2
	s_add_u32 vcc_lo, vcc_lo, 0x100
	s_addc_u32 vcc_hi, vcc_hi, 0
	s_add_u32 s3, s3, 0x100
	s_addc_u32 s94, s94, 0
	s_cmp_gt_u32 s95, 29
; #define PG8_STAGE(bufoff, gbase, voff) do { _Pragma("unroll") for (int _i = 0; _i < 2; ++_i) \
;         __builtin_amdgcn_global_load_lds((const unsigned*)((const char*)(gbase) + (voff)[_i]), (PG8_LAS unsigned*)(lds + (bufoff) + ldsw + _i * 8192), 16, 0, 0); } while (0)
; #define PG8_LDA(dst, b, h) do { _Pragma("unroll") for (int m = 0; m < 4; ++m) _Pragma("unroll") for (int k = 0; k < 2; ++k) dst[m][k] = *(const PG8_LAS bf16x8*)(lds + PG8_SA(b, h) + aoff + m * 2048 + k * 1024); } while (0)
; #define PG8_LDB(dst, b, h) do { _Pragma("unroll") for (int n = 0; n < 2; ++n) _Pragma("unroll") for (int k = 0; k < 2; ++k) dst[n][k] = *(const PG8_LAS bf16x8*)(lds + PG8_SB(b, h) + boff + n * 2048 + k * 1024); } while (0)
; #define PG8_MMA(ai, bj, At, Bt) do { __builtin_amdgcn_s_setprio(1); _Pragma("unroll") for (int m = 0; m < 4; ++m) _Pragma("unroll") for (int n = 0; n < 2; ++n) _Pragma("unroll") for (int k = 0; k < 2; ++k) \
;         acc[ai][bj][m][n] = __builtin_amdgcn_mfma_f32_16x16x32_bf16(Bt[n][k], At[m][k], acc[ai][bj][m][n], 0, 0, 0); __builtin_amdgcn_s_setprio(0); } while (0)
; #define PG8_WAIT_V(n) asm volatile("s_waitcnt vmcnt(" #n ")" ::: "memory")
; #define PG8_WAIT_L(n) asm volatile("s_waitcnt lgkmcnt(" #n ")" ::: "memory")
; #define PG8_BAR __builtin_amdgcn_s_barrier()
; #define PG8_SCHED __builtin_amdgcn_sched_barrier(0)
; template <class Epi, class Sched, bool ALIGN_EPI = false, bool SP2 = false>
; __device__ __forceinline__ void gemm_phase(PG8_LAS unsigned char* lds, const Gemm g, const Sched& S, const Epi& E) {
;     ...
;             PG8_LDB(B0, 0, 0); PG8_LDB(B1, 0, 1); PG8_SCHED; PG8_LDA(At, 0, 0); PG8_STAGE(PG8_SA(1, 1), a1 + hstep, voffA);
;             PG8_WAIT_V(8); PG8_WAIT_L(0); PG8_BAR; PG8_MMA(0, 0, At, B0); PG8_MMA(0, 1, At, B1); PG8_BAR; PG8_SCHED;
;             PG8_LDA(At, 0, 1); PG8_STAGE(PG8_SB(0, 0), b2, voffB); PG8_STAGE(PG8_SB(0, 1), b2 + hstep, voffB); PG8_STAGE(PG8_SA(0, 0), a2, voffA);
;             PG8_WAIT_V(8); PG8_WAIT_L(0); PG8_BAR; PG8_MMA(1, 0, At, B0); PG8_MMA(1, 1, At, B1); PG8_BAR; PG8_SCHED;
.LBB0_298:
	s_add_u32 s36, vcc_lo, 0xfff80080
	s_addc_u32 s37, vcc_hi, -1
	s_add_i32 s38, 0, 0x10000
	s_cmp_eq_u32 s95, 28
	s_cselect_b32 s71, s65, s37
	s_cselect_b32 s70, s67, s36
	s_cselect_b32 s69, s73, s94
	s_cselect_b32 s68, s75, s3
	s_add_i32 s39, 0, 0x14000
	ds_read_b128 v[64:67], v214
	ds_read_b128 v[68:71], v214 offset:1024
	ds_read_b128 v[72:75], v214 offset:2048
	ds_read_b128 v[146:149], v214 offset:3072
	ds_read_b128 v[150:153], v214 offset:16384
	ds_read_b128 v[154:157], v214 offset:17408
	ds_read_b128 v[158:161], v214 offset:18432
	ds_read_b128 v[170:173], v214 offset:19456
	s_add_i32 m0, s88, 0xc000
	ds_read_b128 v[174:177], v169
	ds_read_b128 v[178:181], v169 offset:1024
	ds_read_b128 v[182:185], v169 offset:2048
	ds_read_b128 v[194:197], v169 offset:3072
	ds_read_b128 v[198:201], v169 offset:4096
	ds_read_b128 v[202:205], v169 offset:5120
	ds_read_b128 v[206:209], v169 offset:6144
	ds_read_b128 v[210:213], v169 offset:7168
	global_load_lds_dwordx4 v142, vcc
	s_add_i32 m0, s88, 0xe000
	s_nop 0
	global_load_lds_dwordx4 v144, vcc
	s_waitcnt vmcnt(8)
	s_waitcnt lgkmcnt(0)
	s_barrier
	s_setprio 1
	s_waitcnt lgkmcnt(0)
	v_mfma_f32_16x16x32_bf16 v[136:139], v[64:67], v[174:177], v[136:139]
	v_mfma_f32_16x16x32_bf16 v[136:139], v[68:71], v[178:181], v[136:139]
	v_mfma_f32_16x16x32_bf16 v[132:135], v[72:75], v[174:177], v[132:135]
	v_mfma_f32_16x16x32_bf16 v[132:135], v[146:149], v[178:181], v[132:135]
	v_mfma_f32_16x16x32_bf16 v[120:123], v[64:67], v[182:185], v[120:123]
	v_mfma_f32_16x16x32_bf16 v[120:123], v[68:71], v[194:197], v[120:123]
	v_mfma_f32_16x16x32_bf16 v[116:119], v[72:75], v[182:185], v[116:119]
	v_mfma_f32_16x16x32_bf16 v[116:119], v[146:149], v[194:197], v[116:119]
	v_mfma_f32_16x16x32_bf16 v[104:107], v[64:67], v[198:201], v[104:107]
	v_mfma_f32_16x16x32_bf16 v[104:107], v[68:71], v[202:205], v[104:107]
	v_mfma_f32_16x16x32_bf16 v[100:103], v[72:75], v[198:201], v[100:103]
	v_mfma_f32_16x16x32_bf16 v[100:103], v[146:149], v[202:205], v[100:103]
	v_mfma_f32_16x16x32_bf16 v[88:91], v[64:67], v[206:209], v[88:91]
	v_mfma_f32_16x16x32_bf16 v[88:91], v[68:71], v[210:213], v[88:91]
	v_mfma_f32_16x16x32_bf16 v[84:87], v[72:75], v[206:209], v[84:87]
	v_mfma_f32_16x16x32_bf16 v[84:87], v[146:149], v[210:213], v[84:87]
	v_mfma_f32_16x16x32_bf16 v[128:131], v[150:153], v[174:177], v[128:131]
	v_mfma_f32_16x16x32_bf16 v[128:131], v[154:157], v[178:181], v[128:131]
	v_mfma_f32_16x16x32_bf16 v[124:127], v[158:161], v[174:177], v[124:127]
	v_mfma_f32_16x16x32_bf16 v[124:127], v[170:173], v[178:181], v[124:127]
	v_mfma_f32_16x16x32_bf16 v[112:115], v[150:153], v[182:185], v[112:115]
	v_mfma_f32_16x16x32_bf16 v[112:115], v[154:157], v[194:197], v[112:115]
	v_mfma_f32_16x16x32_bf16 v[108:111], v[158:161], v[182:185], v[108:111]
	v_mfma_f32_16x16x32_bf16 v[108:111], v[170:173], v[194:197], v[108:111]
	v_mfma_f32_16x16x32_bf16 v[96:99], v[150:153], v[198:201], v[96:99]
	v_mfma_f32_16x16x32_bf16 v[96:99], v[154:157], v[202:205], v[96:99]
	v_mfma_f32_16x16x32_bf16 v[92:95], v[158:161], v[198:201], v[92:95]
	v_mfma_f32_16x16x32_bf16 v[92:95], v[170:173], v[202:205], v[92:95]
	v_mfma_f32_16x16x32_bf16 v[80:83], v[150:153], v[206:209], v[80:83]
	v_mfma_f32_16x16x32_bf16 v[80:83], v[154:157], v[210:213], v[80:83]
	v_mfma_f32_16x16x32_bf16 v[76:79], v[158:161], v[206:209], v[76:79]
	v_mfma_f32_16x16x32_bf16 v[76:79], v[170:173], v[210:213], v[76:79]
	s_setprio 0
	s_barrier
	s_add_i32 s36, s38, s87
	s_mov_b32 m0, s36
	ds_read_b128 v[174:177], v169 offset:16384
	ds_read_b128 v[178:181], v169 offset:17408
	ds_read_b128 v[182:185], v169 offset:18432
	ds_read_b128 v[194:197], v169 offset:19456
	ds_read_b128 v[198:201], v169 offset:20480
	ds_read_b128 v[202:205], v169 offset:21504
	ds_read_b128 v[206:209], v169 offset:22528
	ds_read_b128 v[210:213], v169 offset:23552
	global_load_lds_dwordx4 v188, s[68:69]
	s_add_i32 m0, s36, 0x2000
	s_add_u32 s36, s68, 0x80000
	s_addc_u32 s37, s69, 0
	s_add_i32 s38, s39, s87
	global_load_lds_dwordx4 v140, s[68:69]
	s_mov_b32 m0, s38
	s_nop 0
	global_load_lds_dwordx4 v188, s[36:37]
	s_add_i32 m0, s38, 0x2000
	s_nop 0
	global_load_lds_dwordx4 v140, s[36:37]
	s_mov_b32 m0, s88
	s_nop 0
	global_load_lds_dwordx4 v188, s[70:71]
	s_mov_b32 m0, s89
	s_nop 0
	global_load_lds_dwordx4 v140, s[70:71]
	s_waitcnt vmcnt(8)
	s_waitcnt lgkmcnt(0)
	s_barrier
	s_setprio 1
	s_waitcnt lgkmcnt(0)
	v_mfma_f32_16x16x32_bf16 v[56:59], v[64:67], v[174:177], v[56:59]
	v_mfma_f32_16x16x32_bf16 v[56:59], v[68:71], v[178:181], v[56:59]
	v_mfma_f32_16x16x32_bf16 v[60:63], v[72:75], v[174:177], v[60:63]
	v_mfma_f32_16x16x32_bf16 v[60:63], v[146:149], v[178:181], v[60:63]
	v_mfma_f32_16x16x32_bf16 v[40:43], v[64:67], v[182:185], v[40:43]
	v_mfma_f32_16x16x32_bf16 v[40:43], v[68:71], v[194:197], v[40:43]
	v_mfma_f32_16x16x32_bf16 v[44:47], v[72:75], v[182:185], v[44:47]
	v_mfma_f32_16x16x32_bf16 v[44:47], v[146:149], v[194:197], v[44:47]
	v_mfma_f32_16x16x32_bf16 v[24:27], v[64:67], v[198:201], v[24:27]
	v_mfma_f32_16x16x32_bf16 v[24:27], v[68:71], v[202:205], v[24:27]
	v_mfma_f32_16x16x32_bf16 v[28:31], v[72:75], v[198:201], v[28:31]
	v_mfma_f32_16x16x32_bf16 v[28:31], v[146:149], v[202:205], v[28:31]
	v_mfma_f32_16x16x32_bf16 v[8:11], v[64:67], v[206:209], v[8:11]
	v_mfma_f32_16x16x32_bf16 v[8:11], v[68:71], v[210:213], v[8:11]
	v_mfma_f32_16x16x32_bf16 v[12:15], v[72:75], v[206:209], v[12:15]
	v_mfma_f32_16x16x32_bf16 v[12:15], v[146:149], v[210:213], v[12:15]
	v_mfma_f32_16x16x32_bf16 v[52:55], v[150:153], v[174:177], v[52:55]
	v_mfma_f32_16x16x32_bf16 v[52:55], v[154:157], v[178:181], v[52:55]
	v_mfma_f32_16x16x32_bf16 v[48:51], v[158:161], v[174:177], v[48:51]
	v_mfma_f32_16x16x32_bf16 v[48:51], v[170:173], v[178:181], v[48:51]
	v_mfma_f32_16x16x32_bf16 v[36:39], v[150:153], v[182:185], v[36:39]
	v_mfma_f32_16x16x32_bf16 v[36:39], v[154:157], v[194:197], v[36:39]
	v_mfma_f32_16x16x32_bf16 v[32:35], v[158:161], v[182:185], v[32:35]
	v_mfma_f32_16x16x32_bf16 v[32:35], v[170:173], v[194:197], v[32:35]
	v_mfma_f32_16x16x32_bf16 v[20:23], v[150:153], v[198:201], v[20:23]
	v_mfma_f32_16x16x32_bf16 v[20:23], v[154:157], v[202:205], v[20:23]
	v_mfma_f32_16x16x32_bf16 v[16:19], v[158:161], v[198:201], v[16:19]
	v_mfma_f32_16x16x32_bf16 v[16:19], v[170:173], v[202:205], v[16:19]
	v_mfma_f32_16x16x32_bf16 v[4:7], v[150:153], v[206:209], v[4:7]
	v_mfma_f32_16x16x32_bf16 v[4:7], v[154:157], v[210:213], v[4:7]
	v_mfma_f32_16x16x32_bf16 v[0:3], v[158:161], v[206:209], v[0:3]
	v_mfma_f32_16x16x32_bf16 v[0:3], v[170:173], v[210:213], v[0:3]
	s_setprio 0
	s_barrier
; #define PG8_STAGE(bufoff, gbase, voff) do { _Pragma("unroll") for (int _i = 0; _i < 2; ++_i) \
;         __builtin_amdgcn_global_load_lds((const unsigned*)((const char*)(gbase) + (voff)[_i]), (PG8_LAS unsigned*)(lds + (bufoff) + ldsw + _i * 8192), 16, 0, 0); } while (0)
; #define PG8_LDA(dst, b, h) do { _Pragma("unroll") for (int m = 0; m < 4; ++m) _Pragma("unroll") for (int k = 0; k < 2; ++k) dst[m][k] = *(const PG8_LAS bf16x8*)(lds + PG8_SA(b, h) + aoff + m * 2048 + k * 1024); } while (0)
; #define PG8_LDB(dst, b, h) do { _Pragma("unroll") for (int n = 0; n < 2; ++n) _Pragma("unroll") for (int k = 0; k < 2; ++k) dst[n][k] = *(const PG8_LAS bf16x8*)(lds + PG8_SB(b, h) + boff + n * 2048 + k * 1024); } while (0)
; #define PG8_MMA(ai, bj, At, Bt) do { __builtin_amdgcn_s_setprio(1); _Pragma("unroll") for (int m = 0; m < 4; ++m) _Pragma("unroll") for (int n = 0; n < 2; ++n) _Pragma("unroll") for (int k = 0; k < 2; ++k) \
;         acc[ai][bj][m][n] = __builtin_amdgcn_mfma_f32_16x16x32_bf16(Bt[n][k], At[m][k], acc[ai][bj][m][n], 0, 0, 0); __builtin_amdgcn_s_setprio(0); } while (0)
; #define PG8_WAIT_V(n) asm volatile("s_waitcnt vmcnt(" #n ")" ::: "memory")
; #define PG8_WAIT_L(n) asm volatile("s_waitcnt lgkmcnt(" #n ")" ::: "memory")
; #define PG8_BAR __builtin_amdgcn_s_barrier()
; #define PG8_SCHED __builtin_amdgcn_sched_barrier(0)
; template <class Epi, class Sched, bool ALIGN_EPI = false, bool SP2 = false>
; __device__ __forceinline__ void gemm_phase(PG8_LAS unsigned char* lds, const Gemm g, const Sched& S, const Epi& E) {
;     ...
;             PG8_LDB(B0, 1, 0); PG8_LDB(B1, 1, 1); PG8_SCHED; PG8_LDA(At, 1, 0); PG8_STAGE(PG8_SA(0, 1), a2 + hstep, voffA);
;             PG8_WAIT_V(8); PG8_WAIT_L(0); PG8_BAR; PG8_MMA(0, 0, At, B0); PG8_MMA(0, 1, At, B1); PG8_BAR; PG8_SCHED;
	s_add_i32 s38, 0, 0x18000
	s_add_i32 s39, 0, 0x1c000
	ds_read_b128 v[64:67], v214 offset:32768
	ds_read_b128 v[68:71], v214 offset:33792
	ds_read_b128 v[72:75], v214 offset:34816
	ds_read_b128 v[146:149], v214 offset:35840
	ds_read_b128 v[150:153], v214 offset:49152
	ds_read_b128 v[154:157], v214 offset:50176
	ds_read_b128 v[158:161], v214 offset:51200
	ds_read_b128 v[170:173], v214 offset:52224
	s_add_u32 s36, s70, 0x80000
	s_addc_u32 s37, s71, 0
	s_mov_b32 m0, s14
	ds_read_b128 v[174:177], v169 offset:32768
	ds_read_b128 v[178:181], v169 offset:33792
	ds_read_b128 v[182:185], v169 offset:34816
	ds_read_b128 v[194:197], v169 offset:35840
	ds_read_b128 v[198:201], v169 offset:36864
	ds_read_b128 v[202:205], v169 offset:37888
	ds_read_b128 v[206:209], v169 offset:38912
	ds_read_b128 v[210:213], v169 offset:39936
	global_load_lds_dwordx4 v188, s[36:37]
	s_mov_b32 m0, s15
	s_nop 0
	global_load_lds_dwordx4 v140, s[36:37]
	s_waitcnt vmcnt(8)
	s_waitcnt lgkmcnt(0)
	s_barrier
	s_setprio 1
	s_waitcnt lgkmcnt(0)
	v_mfma_f32_16x16x32_bf16 v[136:139], v[64:67], v[174:177], v[136:139]
	v_mfma_f32_16x16x32_bf16 v[136:139], v[68:71], v[178:181], v[136:139]
	v_mfma_f32_16x16x32_bf16 v[132:135], v[72:75], v[174:177], v[132:135]
	v_mfma_f32_16x16x32_bf16 v[132:135], v[146:149], v[178:181], v[132:135]
	v_mfma_f32_16x16x32_bf16 v[120:123], v[64:67], v[182:185], v[120:123]
	v_mfma_f32_16x16x32_bf16 v[120:123], v[68:71], v[194:197], v[120:123]
	v_mfma_f32_16x16x32_bf16 v[116:119], v[72:75], v[182:185], v[116:119]
	v_mfma_f32_16x16x32_bf16 v[116:119], v[146:149], v[194:197], v[116:119]
	v_mfma_f32_16x16x32_bf16 v[104:107], v[64:67], v[198:201], v[104:107]
	v_mfma_f32_16x16x32_bf16 v[104:107], v[68:71], v[202:205], v[104:107]
	v_mfma_f32_16x16x32_bf16 v[100:103], v[72:75], v[198:201], v[100:103]
	v_mfma_f32_16x16x32_bf16 v[100:103], v[146:149], v[202:205], v[100:103]
	v_mfma_f32_16x16x32_bf16 v[88:91], v[64:67], v[206:209], v[88:91]
	v_mfma_f32_16x16x32_bf16 v[88:91], v[68:71], v[210:213], v[88:91]
	v_mfma_f32_16x16x32_bf16 v[84:87], v[72:75], v[206:209], v[84:87]
	v_mfma_f32_16x16x32_bf16 v[84:87], v[146:149], v[210:213], v[84:87]
	v_mfma_f32_16x16x32_bf16 v[128:131], v[150:153], v[174:177], v[128:131]
	v_mfma_f32_16x16x32_bf16 v[128:131], v[154:157], v[178:181], v[128:131]
	v_mfma_f32_16x16x32_bf16 v[124:127], v[158:161], v[174:177], v[124:127]
	v_mfma_f32_16x16x32_bf16 v[124:127], v[170:173], v[178:181], v[124:127]
	v_mfma_f32_16x16x32_bf16 v[112:115], v[150:153], v[182:185], v[112:115]
	v_mfma_f32_16x16x32_bf16 v[112:115], v[154:157], v[194:197], v[112:115]
	v_mfma_f32_16x16x32_bf16 v[108:111], v[158:161], v[182:185], v[108:111]
	v_mfma_f32_16x16x32_bf16 v[108:111], v[170:173], v[194:197], v[108:111]
	v_mfma_f32_16x16x32_bf16 v[96:99], v[150:153], v[198:201], v[96:99]
	v_mfma_f32_16x16x32_bf16 v[96:99], v[154:157], v[202:205], v[96:99]
	v_mfma_f32_16x16x32_bf16 v[92:95], v[158:161], v[198:201], v[92:95]
	v_mfma_f32_16x16x32_bf16 v[92:95], v[170:173], v[202:205], v[92:95]
	v_mfma_f32_16x16x32_bf16 v[80:83], v[150:153], v[206:209], v[80:83]
	v_mfma_f32_16x16x32_bf16 v[80:83], v[154:157], v[210:213], v[80:83]
	v_mfma_f32_16x16x32_bf16 v[76:79], v[158:161], v[206:209], v[76:79]
	v_mfma_f32_16x16x32_bf16 v[76:79], v[170:173], v[210:213], v[76:79]
	s_setprio 0
	s_barrier
; #define PG8_WAIT_V(n) asm volatile("s_waitcnt vmcnt(" #n ")" ::: "memory")
; #define PG8_BAR __builtin_amdgcn_s_barrier()
;     __device__ __forceinline__ void operator()(const f32x4 (&acc)[2][2][4][2], const Unit& u, int wr, int wc, int fr, int fq) const {
;         const int r0 = u.pm * BM + wr * 64 + fr, ch = 64 * u.pn + 16 * wc + 4 * fq, lane = fq * 16 + fr;
;         float rstd[2][4];
; #pragma unroll
;         for (int ai = 0; ai < 2; ++ai)
; #pragma unroll
;             for (int m = 0; m < 4; ++m) rstd[ai][m] = (float)ss[r0 + ai * HALF + m * 16] * (1.f / 16777216.f);
; template <class Epi, class Sched, bool ALIGN_EPI = false, bool SP2 = false>
; __device__ __forceinline__ void gemm_phase(PG8_LAS unsigned char* lds, const Gemm g, const Sched& S, const Epi& E) {
;     ...
;             PG8_LDA(At, 1, 1); PG8_STAGE(PG8_SB(1, 0), b3, voffB); PG8_STAGE(PG8_SB(1, 1), b3 + hstep, voffB); PG8_STAGE(PG8_SA(1, 0), a3, voffA);
;             PG8_WAIT_V(8); PG8_WAIT_L(0); PG8_BAR; PG8_MMA(1, 0, At, B0); PG8_MMA(1, 1, At, B1); PG8_BAR; PG8_SCHED;
;             } else {
;             PG8_LDB(B0, 0, 0); PG8_SCHED; PG8_LDA(At, 0, 0); PG8_STAGE(PG8_SA(1, 1), a1 + hstep, voffA);
;             PG8_WAIT_L(8); PG8_BAR; PG8_WAIT_L(0); PG8_MMA(0, 0, At, B0); PG8_BAR; PG8_SCHED;
;             PG8_LDB(B1, 0, 1); PG8_STAGE(PG8_SB(0, 0), b2, voffB);
;             PG8_BAR; PG8_WAIT_L(0); PG8_MMA(0, 1, At, B1); PG8_BAR;
;             PG8_LDA(At, 0, 1); PG8_STAGE(PG8_SA(0, 0), a2, voffA);
;             PG8_BAR; PG8_WAIT_L(0); PG8_MMA(1, 0, At, B0); PG8_BAR; PG8_SCHED;
;             PG8_STAGE(PG8_SB(0, 1), b2 + hstep, voffB);
;             PG8_WAIT_V(6); PG8_BAR; PG8_MMA(1, 1, At, B1); PG8_BAR;
;             PG8_LDB(B0, 1, 0); PG8_SCHED; PG8_LDA(At, 1, 0); PG8_STAGE(PG8_SA(0, 1), a2 + hstep, voffA);
;             PG8_WAIT_L(8); PG8_BAR; PG8_WAIT_L(0); PG8_MMA(0, 0, At, B0); PG8_BAR; PG8_SCHED;
;             PG8_LDB(B1, 1, 1); PG8_STAGE(PG8_SB(1, 0), b3, voffB);
;             PG8_BAR; PG8_WAIT_L(0); PG8_MMA(0, 1, At, B1); PG8_BAR;
;             PG8_LDA(At, 1, 1); PG8_STAGE(PG8_SA(1, 0), a3, voffA);
;             PG8_BAR; PG8_WAIT_L(0); PG8_MMA(1, 0, At, B0); PG8_BAR; PG8_SCHED;
;             PG8_STAGE(PG8_SB(1, 1), b3 + hstep, voffB);
;             PG8_WAIT_V(6); PG8_BAR; PG8_MMA(1, 1, At, B1); PG8_BAR;
;             }
;         }
;         if constexpr (ALIGN_EPI) { if (wr == 0) PG8_BAR; }
	s_add_i32 s36, s38, s87
	s_mov_b32 m0, s36
	ds_read_b128 v[174:177], v169 offset:49152
	ds_read_b128 v[178:181], v169 offset:50176
	ds_read_b128 v[182:185], v169 offset:51200
	ds_read_b128 v[194:197], v169 offset:52224
	ds_read_b128 v[198:201], v169 offset:53248
	ds_read_b128 v[202:205], v169 offset:54272
	ds_read_b128 v[206:209], v169 offset:55296
	ds_read_b128 v[210:213], v169 offset:56320
	s_add_u32 s100, s68, 0x80
	s_addc_u32 s101, s69, 0
	global_load_lds_dwordx4 v188, s[100:101]
	s_add_i32 m0, s36, 0x2000
	s_add_u32 s36, s68, 0x80080
	s_addc_u32 s37, s69, 0
	s_add_i32 s38, s39, s87
	global_load_lds_dwordx4 v140, s[100:101]
	s_mov_b32 m0, s38
	s_nop 0
	global_load_lds_dwordx4 v188, s[36:37]
	s_add_i32 m0, s38, 0x2000
	s_nop 0
	global_load_lds_dwordx4 v140, s[36:37]
	s_mov_b32 m0, s81
	s_nop 0
	s_add_u32 s100, s70, 0x80
	s_addc_u32 s101, s71, 0
	global_load_lds_dwordx4 v188, s[100:101]
	s_mov_b32 m0, s80
	s_nop 0
	global_load_lds_dwordx4 v140, s[100:101]
	s_waitcnt vmcnt(8)
	s_waitcnt lgkmcnt(0)
	s_barrier
	s_setprio 1
	s_waitcnt lgkmcnt(0)
	v_mfma_f32_16x16x32_bf16 v[56:59], v[64:67], v[174:177], v[56:59]
	v_mfma_f32_16x16x32_bf16 v[56:59], v[68:71], v[178:181], v[56:59]
	v_mfma_f32_16x16x32_bf16 v[60:63], v[72:75], v[174:177], v[60:63]
	v_mfma_f32_16x16x32_bf16 v[60:63], v[146:149], v[178:181], v[60:63]
	v_mfma_f32_16x16x32_bf16 v[40:43], v[64:67], v[182:185], v[40:43]
	v_mfma_f32_16x16x32_bf16 v[40:43], v[68:71], v[194:197], v[40:43]
	v_mfma_f32_16x16x32_bf16 v[44:47], v[72:75], v[182:185], v[44:47]
	v_mfma_f32_16x16x32_bf16 v[44:47], v[146:149], v[194:197], v[44:47]
	v_mfma_f32_16x16x32_bf16 v[24:27], v[64:67], v[198:201], v[24:27]
	v_mfma_f32_16x16x32_bf16 v[24:27], v[68:71], v[202:205], v[24:27]
	v_mfma_f32_16x16x32_bf16 v[28:31], v[72:75], v[198:201], v[28:31]
	v_mfma_f32_16x16x32_bf16 v[28:31], v[146:149], v[202:205], v[28:31]
	v_mfma_f32_16x16x32_bf16 v[8:11], v[64:67], v[206:209], v[8:11]
	v_mfma_f32_16x16x32_bf16 v[8:11], v[68:71], v[210:213], v[8:11]
	v_mfma_f32_16x16x32_bf16 v[12:15], v[72:75], v[206:209], v[12:15]
	v_mfma_f32_16x16x32_bf16 v[12:15], v[146:149], v[210:213], v[12:15]
	v_mfma_f32_16x16x32_bf16 v[52:55], v[150:153], v[174:177], v[52:55]
	v_mfma_f32_16x16x32_bf16 v[52:55], v[154:157], v[178:181], v[52:55]
	v_mfma_f32_16x16x32_bf16 v[48:51], v[158:161], v[174:177], v[48:51]
	v_mfma_f32_16x16x32_bf16 v[48:51], v[170:173], v[178:181], v[48:51]
	v_mfma_f32_16x16x32_bf16 v[36:39], v[150:153], v[182:185], v[36:39]
	v_mfma_f32_16x16x32_bf16 v[36:39], v[154:157], v[194:197], v[36:39]
	v_mfma_f32_16x16x32_bf16 v[32:35], v[158:161], v[182:185], v[32:35]
	v_mfma_f32_16x16x32_bf16 v[32:35], v[170:173], v[194:197], v[32:35]
	v_mfma_f32_16x16x32_bf16 v[20:23], v[150:153], v[198:201], v[20:23]
	v_mfma_f32_16x16x32_bf16 v[20:23], v[154:157], v[202:205], v[20:23]
	v_mfma_f32_16x16x32_bf16 v[16:19], v[158:161], v[198:201], v[16:19]
	v_mfma_f32_16x16x32_bf16 v[16:19], v[170:173], v[202:205], v[16:19]
	v_mfma_f32_16x16x32_bf16 v[4:7], v[150:153], v[206:209], v[4:7]
	v_mfma_f32_16x16x32_bf16 v[4:7], v[154:157], v[210:213], v[4:7]
	v_mfma_f32_16x16x32_bf16 v[0:3], v[158:161], v[206:209], v[0:3]
	v_mfma_f32_16x16x32_bf16 v[0:3], v[170:173], v[210:213], v[0:3]
	s_setprio 0
	s_barrier
	s_add_i32 s95, s95, 2
	s_add_u32 vcc_lo, vcc_lo, 0x100
	s_addc_u32 vcc_hi, vcc_hi, 0
	s_add_u32 s3, s3, 0x100
	s_addc_u32 s94, s94, 0
	s_cmp_gt_u32 s95, 29
	s_cbranch_scc0 .LBB0_298
	v_lshl_add_u32 v148, s72, 8, v164
	v_ashrrev_i32_e32 v149, 31, v148
	v_lshl_add_u64 v[64:65], v[148:149], 3, s[92:93]
	global_load_dwordx2 v[66:67], v[64:65], off
	global_load_dwordx2 v[194:195], v[64:65], off offset:128
	global_load_dwordx2 v[196:197], v[64:65], off offset:256
	global_load_dwordx2 v[198:199], v[64:65], off offset:384
	s_and_b64 vcc, exec, s[58:59]
	s_cbranch_vccz .LBB0_301
	s_barrier

; #define PG8_STAGE(bufoff, gbase, voff) do { _Pragma("unroll") for (int _i = 0; _i < 2; ++_i) \
;         __builtin_amdgcn_global_load_lds((const unsigned*)((const char*)(gbase) + (voff)[_i]), (PG8_LAS unsigned*)(lds + (bufoff) + ldsw + _i * 8192), 16, 0, 0); } while (0)
; #define PG8_LDA(dst, b, h) do { _Pragma("unroll") for (int m = 0; m < 4; ++m) _Pragma("unroll") for (int k = 0; k < 2; ++k) dst[m][k] = *(const PG8_LAS bf16x8*)(lds + PG8_SA(b, h) + aoff + m * 2048 + k * 1024); } while (0)
; #define PG8_LDB(dst, b, h) do { _Pragma("unroll") for (int n = 0; n < 2; ++n) _Pragma("unroll") for (int k = 0; k < 2; ++k) dst[n][k] = *(const PG8_LAS bf16x8*)(lds + PG8_SB(b, h) + boff + n * 2048 + k * 1024); } while (0)
; #define PG8_WAIT_V(n) asm volatile("s_waitcnt vmcnt(" #n ")" ::: "memory")
; #define PG8_WAIT_L(n) asm volatile("s_waitcnt lgkmcnt(" #n ")" ::: "memory")
; #define PG8_BAR __builtin_amdgcn_s_barrier()
; #define PG8_SCHED __builtin_amdgcn_sched_barrier(0)
; template <class Epi, class Sched, bool ALIGN_EPI = false, bool SP2 = false>
; __device__ __forceinline__ void gemm_phase(PG8_LAS unsigned char* lds, const Gemm g, const Sched& S, const Epi& E) {
;     ...
;         const char* nA = has_next ? (const char*)g.A + (size_t)nxt.pm * tstep : cA; const char* nB = has_next ? (const char*)g.Bt + (size_t)nxt.pn * tstep : cB;
;         for (int t = 0; t < nt; t += 2) {
;             const bool last = (t == nt - 2);
;             const char* a1 = cA + (size_t)(t + 1) * kstep;
;             const char* a2 = last ? nA : cA + (size_t)(t + 2) * kstep; const char* b2 = last ? nB : cB + (size_t)(t + 2) * kstep;
;             const char* a3 = a2 + kstep; const char* b3 = b2 + kstep;
;             if (last && has_next) S.a_ready(nxt);
;             if constexpr (SP2) {
;             PG8_LDB(B0, 0, 0); PG8_LDB(B1, 0, 1); PG8_SCHED; PG8_LDA(At, 0, 0); PG8_STAGE(PG8_SA(1, 1), a1 + hstep, voffA);
;             PG8_WAIT_V(8); PG8_WAIT_L(0); PG8_BAR; PG8_MMA(0, 0, At, B0); PG8_MMA(0, 1, At, B1); PG8_BAR; PG8_SCHED;
;             PG8_LDA(At, 0, 1); PG8_STAGE(PG8_SB(0, 0), b2, voffB); PG8_STAGE(PG8_SB(0, 1), b2 + hstep, voffB); PG8_STAGE(PG8_SA(0, 0), a2, voffA);
;             PG8_WAIT_V(8); PG8_WAIT_L(0); PG8_BAR; PG8_MMA(1, 0, At, B0); PG8_MMA(1, 1, At, B1); PG8_BAR; PG8_SCHED;
.LBB0_343:
	s_ashr_i32 s57, s56, 31
	s_lshl_b64 s[14:15], s[56:57], 20
	s_add_u32 s44, s34, s14
	s_addc_u32 s45, s35, s15
	s_and_b64 s[14:15], s[4:5], exec
	s_cselect_b32 s7, s45, s9
	s_cselect_b32 s14, s44, s8
	s_ashr_i32 s61, s60, 31
	s_lshl_b64 s[54:55], s[60:61], 20
	s_add_u32 s58, s68, s54
	s_addc_u32 s59, s69, s55
	s_and_b64 s[54:55], s[4:5], exec
	s_cselect_b32 s15, s59, s11
	s_cselect_b32 s54, s58, s10
	s_add_u32 s8, s8, 0x80080
	s_addc_u32 s9, s9, 0
	s_add_u32 s55, s10, 0x100
	s_addc_u32 s3, s11, 0
	s_mov_b32 s57, -2
	s_nop 0
	s_add_u32 s10, s8, 0xfff80080
	s_addc_u32 s11, s9, -1
	s_add_i32 s36, 0, 0x10000
	s_cmp_eq_u32 s57, 28
	s_cselect_b32 s63, s7, s11
	s_cselect_b32 s62, s14, s10
	s_cselect_b32 s11, s15, s3
	s_cselect_b32 s10, s54, s55
	s_add_i32 s37, 0, 0x14000
	s_add_i32 m0, s53, 0xc000
	global_load_lds_dwordx4 v170, s[8:9]
	s_add_i32 m0, s53, 0xe000
	s_nop 0
	global_load_lds_dwordx4 v172, s[8:9]
	s_waitcnt vmcnt(24)
	s_waitcnt lgkmcnt(0)
	s_barrier
	s_setprio 1
	s_waitcnt lgkmcnt(0)
	v_mfma_f32_16x16x32_bf16 v[124:127], v[128:131], v[174:177], 0
	v_mfma_f32_16x16x32_bf16 v[124:127], v[132:135], v[178:181], v[124:127]
	v_mfma_f32_16x16x32_bf16 v[120:123], v[136:139], v[174:177], 0
	v_mfma_f32_16x16x32_bf16 v[120:123], v[140:143], v[178:181], v[120:123]
	v_mfma_f32_16x16x32_bf16 v[108:111], v[128:131], v[182:185], 0
	v_mfma_f32_16x16x32_bf16 v[108:111], v[132:135], v[194:197], v[108:111]
	v_mfma_f32_16x16x32_bf16 v[104:107], v[136:139], v[182:185], 0
	v_mfma_f32_16x16x32_bf16 v[104:107], v[140:143], v[194:197], v[104:107]
	v_mfma_f32_16x16x32_bf16 v[92:95], v[128:131], v[198:201], 0
	v_mfma_f32_16x16x32_bf16 v[92:95], v[132:135], v[206:209], v[92:95]
	v_mfma_f32_16x16x32_bf16 v[88:91], v[136:139], v[198:201], 0
	v_mfma_f32_16x16x32_bf16 v[88:91], v[140:143], v[206:209], v[88:91]
	v_mfma_f32_16x16x32_bf16 v[76:79], v[128:131], v[210:213], 0
	v_mfma_f32_16x16x32_bf16 v[76:79], v[132:135], v[214:217], v[76:79]
	v_mfma_f32_16x16x32_bf16 v[72:75], v[136:139], v[210:213], 0
	v_mfma_f32_16x16x32_bf16 v[72:75], v[140:143], v[214:217], v[72:75]
	v_mfma_f32_16x16x32_bf16 v[116:119], v[144:147], v[174:177], 0
	v_mfma_f32_16x16x32_bf16 v[116:119], v[148:151], v[178:181], v[116:119]
	v_mfma_f32_16x16x32_bf16 v[112:115], v[152:155], v[174:177], 0
	v_mfma_f32_16x16x32_bf16 v[112:115], v[156:159], v[178:181], v[112:115]
	v_mfma_f32_16x16x32_bf16 v[100:103], v[144:147], v[182:185], 0
	v_mfma_f32_16x16x32_bf16 v[100:103], v[148:151], v[194:197], v[100:103]
	v_mfma_f32_16x16x32_bf16 v[96:99], v[152:155], v[182:185], 0
	v_mfma_f32_16x16x32_bf16 v[96:99], v[156:159], v[194:197], v[96:99]
	v_mfma_f32_16x16x32_bf16 v[84:87], v[144:147], v[198:201], 0
	v_mfma_f32_16x16x32_bf16 v[84:87], v[148:151], v[206:209], v[84:87]
	v_mfma_f32_16x16x32_bf16 v[80:83], v[152:155], v[198:201], 0
	v_mfma_f32_16x16x32_bf16 v[80:83], v[156:159], v[206:209], v[80:83]
	v_mfma_f32_16x16x32_bf16 v[68:71], v[144:147], v[210:213], 0
	v_mfma_f32_16x16x32_bf16 v[68:71], v[148:151], v[214:217], v[68:71]
	v_mfma_f32_16x16x32_bf16 v[64:67], v[152:155], v[210:213], 0
	v_mfma_f32_16x16x32_bf16 v[64:67], v[156:159], v[214:217], v[64:67]
	s_setprio 0
	s_barrier
	s_add_i32 s36, s36, s70
	s_mov_b32 m0, s36
	ds_read_b128 v[174:177], v204 offset:16384
	ds_read_b128 v[178:181], v204 offset:17408
	ds_read_b128 v[182:185], v204 offset:18432
	ds_read_b128 v[194:197], v204 offset:19456
	ds_read_b128 v[198:201], v204 offset:20480
	ds_read_b128 v[206:209], v204 offset:21504
	ds_read_b128 v[210:213], v204 offset:22528
	ds_read_b128 v[214:217], v204 offset:23552
	global_load_lds_dwordx4 v160, s[10:11]
	s_add_i32 m0, s36, 0x2000
	s_add_u32 s64, s10, 0x80000
	s_addc_u32 s65, s11, 0
	s_add_i32 s36, s37, s70
	global_load_lds_dwordx4 v162, s[10:11]
	s_mov_b32 m0, s36
	s_nop 0
	global_load_lds_dwordx4 v160, s[64:65]
	s_add_i32 m0, s36, 0x2000
	s_nop 0
	global_load_lds_dwordx4 v162, s[64:65]
	s_mov_b32 m0, s53
	s_nop 0
	global_load_lds_dwordx4 v160, s[62:63]
	s_mov_b32 m0, s71
	s_nop 0
	global_load_lds_dwordx4 v162, s[62:63]
	s_waitcnt vmcnt(24)
	s_waitcnt lgkmcnt(0)
	s_barrier
	s_setprio 1
	s_waitcnt lgkmcnt(0)
	v_mfma_f32_16x16x32_bf16 v[60:63], v[128:131], v[174:177], 0
	v_mfma_f32_16x16x32_bf16 v[60:63], v[132:135], v[178:181], v[60:63]
	v_mfma_f32_16x16x32_bf16 v[56:59], v[136:139], v[174:177], 0
	v_mfma_f32_16x16x32_bf16 v[56:59], v[140:143], v[178:181], v[56:59]
	v_mfma_f32_16x16x32_bf16 v[44:47], v[128:131], v[182:185], 0
	v_mfma_f32_16x16x32_bf16 v[44:47], v[132:135], v[194:197], v[44:47]
	v_mfma_f32_16x16x32_bf16 v[40:43], v[136:139], v[182:185], 0
	v_mfma_f32_16x16x32_bf16 v[40:43], v[140:143], v[194:197], v[40:43]
	v_mfma_f32_16x16x32_bf16 v[28:31], v[128:131], v[198:201], 0
	v_mfma_f32_16x16x32_bf16 v[28:31], v[132:135], v[206:209], v[28:31]
	v_mfma_f32_16x16x32_bf16 v[24:27], v[136:139], v[198:201], 0
	v_mfma_f32_16x16x32_bf16 v[24:27], v[140:143], v[206:209], v[24:27]
	v_mfma_f32_16x16x32_bf16 v[12:15], v[128:131], v[210:213], 0
	v_mfma_f32_16x16x32_bf16 v[12:15], v[132:135], v[214:217], v[12:15]
	v_mfma_f32_16x16x32_bf16 v[8:11], v[136:139], v[210:213], 0
	v_mfma_f32_16x16x32_bf16 v[8:11], v[140:143], v[214:217], v[8:11]
	v_mfma_f32_16x16x32_bf16 v[52:55], v[144:147], v[174:177], 0
	v_mfma_f32_16x16x32_bf16 v[52:55], v[148:151], v[178:181], v[52:55]
	v_mfma_f32_16x16x32_bf16 v[48:51], v[152:155], v[174:177], 0
	v_mfma_f32_16x16x32_bf16 v[48:51], v[156:159], v[178:181], v[48:51]
	v_mfma_f32_16x16x32_bf16 v[36:39], v[144:147], v[182:185], 0
	v_mfma_f32_16x16x32_bf16 v[36:39], v[148:151], v[194:197], v[36:39]
	v_mfma_f32_16x16x32_bf16 v[32:35], v[152:155], v[182:185], 0
	v_mfma_f32_16x16x32_bf16 v[32:35], v[156:159], v[194:197], v[32:35]
	v_mfma_f32_16x16x32_bf16 v[20:23], v[144:147], v[198:201], 0
	v_mfma_f32_16x16x32_bf16 v[20:23], v[148:151], v[206:209], v[20:23]
	v_mfma_f32_16x16x32_bf16 v[16:19], v[152:155], v[198:201], 0
	v_mfma_f32_16x16x32_bf16 v[16:19], v[156:159], v[206:209], v[16:19]
	v_mfma_f32_16x16x32_bf16 v[4:7], v[144:147], v[210:213], 0
	v_mfma_f32_16x16x32_bf16 v[4:7], v[148:151], v[214:217], v[4:7]
	v_mfma_f32_16x16x32_bf16 v[0:3], v[152:155], v[210:213], 0
	v_mfma_f32_16x16x32_bf16 v[0:3], v[156:159], v[214:217], v[0:3]
	s_setprio 0
	s_barrier
; #define PG8_STAGE(bufoff, gbase, voff) do { _Pragma("unroll") for (int _i = 0; _i < 2; ++_i) \
;         __builtin_amdgcn_global_load_lds((const unsigned*)((const char*)(gbase) + (voff)[_i]), (PG8_LAS unsigned*)(lds + (bufoff) + ldsw + _i * 8192), 16, 0, 0); } while (0)
; #define PG8_LDA(dst, b, h) do { _Pragma("unroll") for (int m = 0; m < 4; ++m) _Pragma("unroll") for (int k = 0; k < 2; ++k) dst[m][k] = *(const PG8_LAS bf16x8*)(lds + PG8_SA(b, h) + aoff + m * 2048 + k * 1024); } while (0)
; #define PG8_LDB(dst, b, h) do { _Pragma("unroll") for (int n = 0; n < 2; ++n) _Pragma("unroll") for (int k = 0; k < 2; ++k) dst[n][k] = *(const PG8_LAS bf16x8*)(lds + PG8_SB(b, h) + boff + n * 2048 + k * 1024); } while (0)
; #define PG8_MMA(ai, bj, At, Bt) do { __builtin_amdgcn_s_setprio(1); _Pragma("unroll") for (int m = 0; m < 4; ++m) _Pragma("unroll") for (int n = 0; n < 2; ++n) _Pragma("unroll") for (int k = 0; k < 2; ++k) \
;         acc[ai][bj][m][n] = __builtin_amdgcn_mfma_f32_16x16x32_bf16(Bt[n][k], At[m][k], acc[ai][bj][m][n], 0, 0, 0); __builtin_amdgcn_s_setprio(0); } while (0)
; #define PG8_WAIT_V(n) asm volatile("s_waitcnt vmcnt(" #n ")" ::: "memory")
; template <class Epi, class Sched, bool ALIGN_EPI = false, bool SP2 = false>
; __device__ __forceinline__ void gemm_phase(PG8_LAS unsigned char* lds, const Gemm g, const Sched& S, const Epi& E) {
;     ...
;             PG8_LDB(B0, 0, 0); PG8_LDB(B1, 0, 1); PG8_SCHED; PG8_LDA(At, 0, 0); PG8_STAGE(PG8_SA(1, 1), a1 + hstep, voffA);
;             PG8_WAIT_V(8); PG8_WAIT_L(0); PG8_BAR; PG8_MMA(0, 0, At, B0); PG8_MMA(0, 1, At, B1); PG8_BAR; PG8_SCHED;
;             PG8_LDA(At, 0, 1); PG8_STAGE(PG8_SB(0, 0), b2, voffB); PG8_STAGE(PG8_SB(0, 1), b2 + hstep, voffB); PG8_STAGE(PG8_SA(0, 0), a2, voffA);
;             PG8_WAIT_V(8); PG8_WAIT_L(0); PG8_BAR; PG8_MMA(1, 0, At, B0); PG8_MMA(1, 1, At, B1); PG8_BAR; PG8_SCHED;
;             PG8_LDB(B0, 1, 0); PG8_LDB(B1, 1, 1); PG8_SCHED; PG8_LDA(At, 1, 0); PG8_STAGE(PG8_SA(0, 1), a2 + hstep, voffA);
;             PG8_WAIT_V(8); PG8_WAIT_L(0); PG8_BAR; PG8_MMA(0, 0, At, B0); PG8_MMA(0, 1, At, B1); PG8_BAR; PG8_SCHED;
;             PG8_LDA(At, 1, 1); PG8_STAGE(PG8_SB(1, 0), b3, voffB); PG8_STAGE(PG8_SB(1, 1), b3 + hstep, voffB); PG8_STAGE(PG8_SA(1, 0), a3, voffA);
;             PG8_WAIT_V(8); PG8_WAIT_L(0); PG8_BAR; PG8_MMA(1, 0, At, B0); PG8_MMA(1, 1, At, B1); PG8_BAR; PG8_SCHED;
	s_add_i32 s36, 0, 0x18000
	s_add_i32 s37, 0, 0x1c000
	ds_read_b128 v[128:131], v218 offset:32768
	ds_read_b128 v[132:135], v218 offset:33792
	ds_read_b128 v[136:139], v218 offset:34816
	ds_read_b128 v[140:143], v218 offset:35840
	ds_read_b128 v[144:147], v218 offset:49152
	ds_read_b128 v[148:151], v218 offset:50176
	ds_read_b128 v[152:155], v218 offset:51200
	ds_read_b128 v[156:159], v218 offset:52224
	s_add_u32 s62, s62, 0x80000
	s_addc_u32 s63, s63, 0
	s_mov_b32 m0, s72
	ds_read_b128 v[174:177], v204 offset:32768
	ds_read_b128 v[178:181], v204 offset:33792
	ds_read_b128 v[182:185], v204 offset:34816
	ds_read_b128 v[194:197], v204 offset:35840
	ds_read_b128 v[198:201], v204 offset:36864
	ds_read_b128 v[206:209], v204 offset:37888
	ds_read_b128 v[210:213], v204 offset:38912
	ds_read_b128 v[214:217], v204 offset:39936
	global_load_lds_dwordx4 v160, s[62:63]
	s_mov_b32 m0, s73
	s_nop 0
	global_load_lds_dwordx4 v162, s[62:63]
	s_waitcnt vmcnt(8)
	s_waitcnt lgkmcnt(0)
	s_barrier
	s_setprio 1
	s_waitcnt lgkmcnt(0)
	v_mfma_f32_16x16x32_bf16 v[124:127], v[128:131], v[174:177], v[124:127]
	v_mfma_f32_16x16x32_bf16 v[124:127], v[132:135], v[178:181], v[124:127]
	v_mfma_f32_16x16x32_bf16 v[120:123], v[136:139], v[174:177], v[120:123]
	v_mfma_f32_16x16x32_bf16 v[120:123], v[140:143], v[178:181], v[120:123]
	v_mfma_f32_16x16x32_bf16 v[108:111], v[128:131], v[182:185], v[108:111]
	v_mfma_f32_16x16x32_bf16 v[108:111], v[132:135], v[194:197], v[108:111]
	v_mfma_f32_16x16x32_bf16 v[104:107], v[136:139], v[182:185], v[104:107]
	v_mfma_f32_16x16x32_bf16 v[104:107], v[140:143], v[194:197], v[104:107]
	v_mfma_f32_16x16x32_bf16 v[92:95], v[128:131], v[198:201], v[92:95]
	v_mfma_f32_16x16x32_bf16 v[92:95], v[132:135], v[206:209], v[92:95]
	v_mfma_f32_16x16x32_bf16 v[88:91], v[136:139], v[198:201], v[88:91]
	v_mfma_f32_16x16x32_bf16 v[88:91], v[140:143], v[206:209], v[88:91]
	v_mfma_f32_16x16x32_bf16 v[76:79], v[128:131], v[210:213], v[76:79]
	v_mfma_f32_16x16x32_bf16 v[76:79], v[132:135], v[214:217], v[76:79]
	v_mfma_f32_16x16x32_bf16 v[72:75], v[136:139], v[210:213], v[72:75]
	v_mfma_f32_16x16x32_bf16 v[72:75], v[140:143], v[214:217], v[72:75]
	v_mfma_f32_16x16x32_bf16 v[116:119], v[144:147], v[174:177], v[116:119]
	v_mfma_f32_16x16x32_bf16 v[116:119], v[148:151], v[178:181], v[116:119]
	v_mfma_f32_16x16x32_bf16 v[112:115], v[152:155], v[174:177], v[112:115]
	v_mfma_f32_16x16x32_bf16 v[112:115], v[156:159], v[178:181], v[112:115]
	v_mfma_f32_16x16x32_bf16 v[100:103], v[144:147], v[182:185], v[100:103]
	v_mfma_f32_16x16x32_bf16 v[100:103], v[148:151], v[194:197], v[100:103]
	v_mfma_f32_16x16x32_bf16 v[96:99], v[152:155], v[182:185], v[96:99]
	v_mfma_f32_16x16x32_bf16 v[96:99], v[156:159], v[194:197], v[96:99]
	v_mfma_f32_16x16x32_bf16 v[84:87], v[144:147], v[198:201], v[84:87]
	v_mfma_f32_16x16x32_bf16 v[84:87], v[148:151], v[206:209], v[84:87]
	v_mfma_f32_16x16x32_bf16 v[80:83], v[152:155], v[198:201], v[80:83]
	v_mfma_f32_16x16x32_bf16 v[80:83], v[156:159], v[206:209], v[80:83]
	v_mfma_f32_16x16x32_bf16 v[68:71], v[144:147], v[210:213], v[68:71]
	v_mfma_f32_16x16x32_bf16 v[68:71], v[148:151], v[214:217], v[68:71]
	v_mfma_f32_16x16x32_bf16 v[64:67], v[152:155], v[210:213], v[64:67]
	v_mfma_f32_16x16x32_bf16 v[64:67], v[156:159], v[214:217], v[64:67]
	s_setprio 0
	s_barrier
	s_add_i32 s36, s36, s70
	s_mov_b32 m0, s36
	ds_read_b128 v[174:177], v204 offset:49152
	ds_read_b128 v[178:181], v204 offset:50176
	ds_read_b128 v[182:185], v204 offset:51200
	ds_read_b128 v[194:197], v204 offset:52224
	ds_read_b128 v[198:201], v204 offset:53248
	ds_read_b128 v[206:209], v204 offset:54272
	ds_read_b128 v[210:213], v204 offset:55296
	ds_read_b128 v[214:217], v204 offset:56320
	s_add_u32 s100, s10, 0x80
	s_addc_u32 s101, s11, 0
	global_load_lds_dwordx4 v160, s[100:101]
	s_add_i32 m0, s36, 0x2000
	s_add_u32 s10, s10, 0x80080
	s_addc_u32 s11, s11, 0
	s_add_i32 s36, s37, s70
	s_add_u32 s100, s10, 0xfff80000
	s_addc_u32 s101, s11, -1
	global_load_lds_dwordx4 v162, s[100:101]
	s_mov_b32 m0, s36
	s_nop 0
	global_load_lds_dwordx4 v160, s[10:11]
	s_add_i32 m0, s36, 0x2000
	s_nop 0
	global_load_lds_dwordx4 v162, s[10:11]
	s_mov_b32 m0, s76
	s_nop 0
	s_add_u32 s100, s62, 0xfff80080
	s_addc_u32 s101, s63, -1
	global_load_lds_dwordx4 v160, s[100:101]
	s_mov_b32 m0, s77
	s_nop 0
	global_load_lds_dwordx4 v162, s[100:101]
	s_waitcnt vmcnt(8)
	s_waitcnt lgkmcnt(0)
	s_barrier
	s_setprio 1
	s_waitcnt lgkmcnt(0)
	v_mfma_f32_16x16x32_bf16 v[60:63], v[128:131], v[174:177], v[60:63]
	v_mfma_f32_16x16x32_bf16 v[60:63], v[132:135], v[178:181], v[60:63]
	v_mfma_f32_16x16x32_bf16 v[56:59], v[136:139], v[174:177], v[56:59]
	v_mfma_f32_16x16x32_bf16 v[56:59], v[140:143], v[178:181], v[56:59]
	v_mfma_f32_16x16x32_bf16 v[44:47], v[128:131], v[182:185], v[44:47]
	v_mfma_f32_16x16x32_bf16 v[44:47], v[132:135], v[194:197], v[44:47]
	v_mfma_f32_16x16x32_bf16 v[40:43], v[136:139], v[182:185], v[40:43]
	v_mfma_f32_16x16x32_bf16 v[40:43], v[140:143], v[194:197], v[40:43]
	v_mfma_f32_16x16x32_bf16 v[28:31], v[128:131], v[198:201], v[28:31]
	v_mfma_f32_16x16x32_bf16 v[28:31], v[132:135], v[206:209], v[28:31]
	v_mfma_f32_16x16x32_bf16 v[24:27], v[136:139], v[198:201], v[24:27]
	v_mfma_f32_16x16x32_bf16 v[24:27], v[140:143], v[206:209], v[24:27]
	v_mfma_f32_16x16x32_bf16 v[12:15], v[128:131], v[210:213], v[12:15]
	v_mfma_f32_16x16x32_bf16 v[12:15], v[132:135], v[214:217], v[12:15]
	v_mfma_f32_16x16x32_bf16 v[8:11], v[136:139], v[210:213], v[8:11]
	v_mfma_f32_16x16x32_bf16 v[8:11], v[140:143], v[214:217], v[8:11]
	v_mfma_f32_16x16x32_bf16 v[52:55], v[144:147], v[174:177], v[52:55]
	v_mfma_f32_16x16x32_bf16 v[52:55], v[148:151], v[178:181], v[52:55]
	v_mfma_f32_16x16x32_bf16 v[48:51], v[152:155], v[174:177], v[48:51]
	v_mfma_f32_16x16x32_bf16 v[48:51], v[156:159], v[178:181], v[48:51]
	v_mfma_f32_16x16x32_bf16 v[36:39], v[144:147], v[182:185], v[36:39]
	v_mfma_f32_16x16x32_bf16 v[36:39], v[148:151], v[194:197], v[36:39]
	v_mfma_f32_16x16x32_bf16 v[32:35], v[152:155], v[182:185], v[32:35]
	v_mfma_f32_16x16x32_bf16 v[32:35], v[156:159], v[194:197], v[32:35]
	v_mfma_f32_16x16x32_bf16 v[20:23], v[144:147], v[198:201], v[20:23]
	v_mfma_f32_16x16x32_bf16 v[20:23], v[148:151], v[206:209], v[20:23]
	v_mfma_f32_16x16x32_bf16 v[16:19], v[152:155], v[198:201], v[16:19]
	v_mfma_f32_16x16x32_bf16 v[16:19], v[156:159], v[206:209], v[16:19]
	v_mfma_f32_16x16x32_bf16 v[4:7], v[144:147], v[210:213], v[4:7]
	v_mfma_f32_16x16x32_bf16 v[4:7], v[148:151], v[214:217], v[4:7]
	v_mfma_f32_16x16x32_bf16 v[0:3], v[152:155], v[210:213], v[0:3]
	v_mfma_f32_16x16x32_bf16 v[0:3], v[156:159], v[214:217], v[0:3]
	s_setprio 0
	s_barrier
	s_add_i32 s57, s57, 2
	s_add_u32 s8, s8, 0x100
	s_addc_u32 s9, s9, 0
	s_add_u32 s55, s55, 0x100
	s_addc_u32 s3, s3, 0
	s_cmp_gt_u32 s57, 29
; #define PG8_STAGE(bufoff, gbase, voff) do { _Pragma("unroll") for (int _i = 0; _i < 2; ++_i) \
;         __builtin_amdgcn_global_load_lds((const unsigned*)((const char*)(gbase) + (voff)[_i]), (PG8_LAS unsigned*)(lds + (bufoff) + ldsw + _i * 8192), 16, 0, 0); } while (0)
; #define PG8_LDA(dst, b, h) do { _Pragma("unroll") for (int m = 0; m < 4; ++m) _Pragma("unroll") for (int k = 0; k < 2; ++k) dst[m][k] = *(const PG8_LAS bf16x8*)(lds + PG8_SA(b, h) + aoff + m * 2048 + k * 1024); } while (0)
; #define PG8_LDB(dst, b, h) do { _Pragma("unroll") for (int n = 0; n < 2; ++n) _Pragma("unroll") for (int k = 0; k < 2; ++k) dst[n][k] = *(const PG8_LAS bf16x8*)(lds + PG8_SB(b, h) + boff + n * 2048 + k * 1024); } while (0)
; #define PG8_MMA(ai, bj, At, Bt) do { __builtin_amdgcn_s_setprio(1); _Pragma("unroll") for (int m = 0; m < 4; ++m) _Pragma("unroll") for (int n = 0; n < 2; ++n) _Pragma("unroll") for (int k = 0; k < 2; ++k) \
;         acc[ai][bj][m][n] = __builtin_amdgcn_mfma_f32_16x16x32_bf16(Bt[n][k], At[m][k], acc[ai][bj][m][n], 0, 0, 0); __builtin_amdgcn_s_setprio(0); } while (0)
; #define PG8_WAIT_V(n) asm volatile("s_waitcnt vmcnt(" #n ")" ::: "memory")
; #define PG8_WAIT_L(n) asm volatile("s_waitcnt lgkmcnt(" #n ")" ::: "memory")
; template <class Epi, class Sched, bool ALIGN_EPI = false, bool SP2 = false>
; __device__ __forceinline__ void gemm_phase(PG8_LAS unsigned char* lds, const Gemm g, const Sched& S, const Epi& E) {
;     ...
;             const bool last = (t == nt - 2);
;             const char* a1 = cA + (size_t)(t + 1) * kstep;
;             const char* a2 = last ? nA : cA + (size_t)(t + 2) * kstep; const char* b2 = last ? nB : cB + (size_t)(t + 2) * kstep;
;             const char* a3 = a2 + kstep; const char* b3 = b2 + kstep;
;             if (last && has_next) S.a_ready(nxt);
;             if constexpr (SP2) {
;             PG8_LDB(B0, 0, 0); PG8_LDB(B1, 0, 1); PG8_SCHED; PG8_LDA(At, 0, 0); PG8_STAGE(PG8_SA(1, 1), a1 + hstep, voffA);
;             PG8_WAIT_V(8); PG8_WAIT_L(0); PG8_BAR; PG8_MMA(0, 0, At, B0); PG8_MMA(0, 1, At, B1); PG8_BAR; PG8_SCHED;
;             PG8_LDA(At, 0, 1); PG8_STAGE(PG8_SB(0, 0), b2, voffB); PG8_STAGE(PG8_SB(0, 1), b2 + hstep, voffB); PG8_STAGE(PG8_SA(0, 0), a2, voffA);
;             PG8_WAIT_V(8); PG8_WAIT_L(0); PG8_BAR; PG8_MMA(1, 0, At, B0); PG8_MMA(1, 1, At, B1); PG8_BAR; PG8_SCHED;
.LBB0_344:
	s_add_u32 s10, s8, 0xfff80080
	s_addc_u32 s11, s9, -1
	s_add_i32 s36, 0, 0x10000
	s_cmp_eq_u32 s57, 28
	s_cselect_b32 s63, s7, s11
	s_cselect_b32 s62, s14, s10
	s_cselect_b32 s11, s15, s3
	s_cselect_b32 s10, s54, s55
	s_add_i32 s37, 0, 0x14000
	ds_read_b128 v[128:131], v218
	ds_read_b128 v[132:135], v218 offset:1024
	ds_read_b128 v[136:139], v218 offset:2048
	ds_read_b128 v[140:143], v218 offset:3072
	ds_read_b128 v[144:147], v218 offset:16384
	ds_read_b128 v[148:151], v218 offset:17408
	ds_read_b128 v[152:155], v218 offset:18432
	ds_read_b128 v[156:159], v218 offset:19456
	s_add_i32 m0, s53, 0xc000
	ds_read_b128 v[174:177], v204
	ds_read_b128 v[178:181], v204 offset:1024
	ds_read_b128 v[182:185], v204 offset:2048
	ds_read_b128 v[194:197], v204 offset:3072
	ds_read_b128 v[198:201], v204 offset:4096
	ds_read_b128 v[206:209], v204 offset:5120
	ds_read_b128 v[210:213], v204 offset:6144
	ds_read_b128 v[214:217], v204 offset:7168
	global_load_lds_dwordx4 v170, s[8:9]
	s_add_i32 m0, s53, 0xe000
	s_nop 0
	global_load_lds_dwordx4 v172, s[8:9]
	s_waitcnt vmcnt(8)
	s_waitcnt lgkmcnt(0)
	s_barrier
	s_setprio 1
	s_waitcnt lgkmcnt(0)
	v_mfma_f32_16x16x32_bf16 v[124:127], v[128:131], v[174:177], v[124:127]
	v_mfma_f32_16x16x32_bf16 v[124:127], v[132:135], v[178:181], v[124:127]
	v_mfma_f32_16x16x32_bf16 v[120:123], v[136:139], v[174:177], v[120:123]
	v_mfma_f32_16x16x32_bf16 v[120:123], v[140:143], v[178:181], v[120:123]
	v_mfma_f32_16x16x32_bf16 v[108:111], v[128:131], v[182:185], v[108:111]
	v_mfma_f32_16x16x32_bf16 v[108:111], v[132:135], v[194:197], v[108:111]
	v_mfma_f32_16x16x32_bf16 v[104:107], v[136:139], v[182:185], v[104:107]
	v_mfma_f32_16x16x32_bf16 v[104:107], v[140:143], v[194:197], v[104:107]
	v_mfma_f32_16x16x32_bf16 v[92:95], v[128:131], v[198:201], v[92:95]
	v_mfma_f32_16x16x32_bf16 v[92:95], v[132:135], v[206:209], v[92:95]
	v_mfma_f32_16x16x32_bf16 v[88:91], v[136:139], v[198:201], v[88:91]
	v_mfma_f32_16x16x32_bf16 v[88:91], v[140:143], v[206:209], v[88:91]
	v_mfma_f32_16x16x32_bf16 v[76:79], v[128:131], v[210:213], v[76:79]
	v_mfma_f32_16x16x32_bf16 v[76:79], v[132:135], v[214:217], v[76:79]
	v_mfma_f32_16x16x32_bf16 v[72:75], v[136:139], v[210:213], v[72:75]
	v_mfma_f32_16x16x32_bf16 v[72:75], v[140:143], v[214:217], v[72:75]
	v_mfma_f32_16x16x32_bf16 v[116:119], v[144:147], v[174:177], v[116:119]
	v_mfma_f32_16x16x32_bf16 v[116:119], v[148:151], v[178:181], v[116:119]
	v_mfma_f32_16x16x32_bf16 v[112:115], v[152:155], v[174:177], v[112:115]
	v_mfma_f32_16x16x32_bf16 v[112:115], v[156:159], v[178:181], v[112:115]
	v_mfma_f32_16x16x32_bf16 v[100:103], v[144:147], v[182:185], v[100:103]
	v_mfma_f32_16x16x32_bf16 v[100:103], v[148:151], v[194:197], v[100:103]
	v_mfma_f32_16x16x32_bf16 v[96:99], v[152:155], v[182:185], v[96:99]
	v_mfma_f32_16x16x32_bf16 v[96:99], v[156:159], v[194:197], v[96:99]
	v_mfma_f32_16x16x32_bf16 v[84:87], v[144:147], v[198:201], v[84:87]
	v_mfma_f32_16x16x32_bf16 v[84:87], v[148:151], v[206:209], v[84:87]
	v_mfma_f32_16x16x32_bf16 v[80:83], v[152:155], v[198:201], v[80:83]
	v_mfma_f32_16x16x32_bf16 v[80:83], v[156:159], v[206:209], v[80:83]
	v_mfma_f32_16x16x32_bf16 v[68:71], v[144:147], v[210:213], v[68:71]
	v_mfma_f32_16x16x32_bf16 v[68:71], v[148:151], v[214:217], v[68:71]
	v_mfma_f32_16x16x32_bf16 v[64:67], v[152:155], v[210:213], v[64:67]
	v_mfma_f32_16x16x32_bf16 v[64:67], v[156:159], v[214:217], v[64:67]
	s_setprio 0
	s_barrier
	s_add_i32 s36, s36, s70
	s_mov_b32 m0, s36
	ds_read_b128 v[174:177], v204 offset:16384
	ds_read_b128 v[178:181], v204 offset:17408
	ds_read_b128 v[182:185], v204 offset:18432
	ds_read_b128 v[194:197], v204 offset:19456
	ds_read_b128 v[198:201], v204 offset:20480
	ds_read_b128 v[206:209], v204 offset:21504
	ds_read_b128 v[210:213], v204 offset:22528
	ds_read_b128 v[214:217], v204 offset:23552
	global_load_lds_dwordx4 v160, s[10:11]
	s_add_i32 m0, s36, 0x2000
	s_add_u32 s64, s10, 0x80000
	s_addc_u32 s65, s11, 0
	s_add_i32 s36, s37, s70
	global_load_lds_dwordx4 v162, s[10:11]
	s_mov_b32 m0, s36
	s_nop 0
	global_load_lds_dwordx4 v160, s[64:65]
	s_add_i32 m0, s36, 0x2000
	s_nop 0
	global_load_lds_dwordx4 v162, s[64:65]
	s_mov_b32 m0, s53
	s_nop 0
	global_load_lds_dwordx4 v160, s[62:63]
	s_mov_b32 m0, s71
	s_nop 0
	global_load_lds_dwordx4 v162, s[62:63]
	s_waitcnt vmcnt(8)
	s_waitcnt lgkmcnt(0)
	s_barrier
	s_setprio 1
	s_waitcnt lgkmcnt(0)
	v_mfma_f32_16x16x32_bf16 v[60:63], v[128:131], v[174:177], v[60:63]
	v_mfma_f32_16x16x32_bf16 v[60:63], v[132:135], v[178:181], v[60:63]
	v_mfma_f32_16x16x32_bf16 v[56:59], v[136:139], v[174:177], v[56:59]
	v_mfma_f32_16x16x32_bf16 v[56:59], v[140:143], v[178:181], v[56:59]
	v_mfma_f32_16x16x32_bf16 v[44:47], v[128:131], v[182:185], v[44:47]
	v_mfma_f32_16x16x32_bf16 v[44:47], v[132:135], v[194:197], v[44:47]
	v_mfma_f32_16x16x32_bf16 v[40:43], v[136:139], v[182:185], v[40:43]
	v_mfma_f32_16x16x32_bf16 v[40:43], v[140:143], v[194:197], v[40:43]
	v_mfma_f32_16x16x32_bf16 v[28:31], v[128:131], v[198:201], v[28:31]
	v_mfma_f32_16x16x32_bf16 v[28:31], v[132:135], v[206:209], v[28:31]
	v_mfma_f32_16x16x32_bf16 v[24:27], v[136:139], v[198:201], v[24:27]
	v_mfma_f32_16x16x32_bf16 v[24:27], v[140:143], v[206:209], v[24:27]
	v_mfma_f32_16x16x32_bf16 v[12:15], v[128:131], v[210:213], v[12:15]
	v_mfma_f32_16x16x32_bf16 v[12:15], v[132:135], v[214:217], v[12:15]
	v_mfma_f32_16x16x32_bf16 v[8:11], v[136:139], v[210:213], v[8:11]
	v_mfma_f32_16x16x32_bf16 v[8:11], v[140:143], v[214:217], v[8:11]
	v_mfma_f32_16x16x32_bf16 v[52:55], v[144:147], v[174:177], v[52:55]
	v_mfma_f32_16x16x32_bf16 v[52:55], v[148:151], v[178:181], v[52:55]
	v_mfma_f32_16x16x32_bf16 v[48:51], v[152:155], v[174:177], v[48:51]
	v_mfma_f32_16x16x32_bf16 v[48:51], v[156:159], v[178:181], v[48:51]
	v_mfma_f32_16x16x32_bf16 v[36:39], v[144:147], v[182:185], v[36:39]
	v_mfma_f32_16x16x32_bf16 v[36:39], v[148:151], v[194:197], v[36:39]
	v_mfma_f32_16x16x32_bf16 v[32:35], v[152:155], v[182:185], v[32:35]
	v_mfma_f32_16x16x32_bf16 v[32:35], v[156:159], v[194:197], v[32:35]
	v_mfma_f32_16x16x32_bf16 v[20:23], v[144:147], v[198:201], v[20:23]
	v_mfma_f32_16x16x32_bf16 v[20:23], v[148:151], v[206:209], v[20:23]
	v_mfma_f32_16x16x32_bf16 v[16:19], v[152:155], v[198:201], v[16:19]
	v_mfma_f32_16x16x32_bf16 v[16:19], v[156:159], v[206:209], v[16:19]
	v_mfma_f32_16x16x32_bf16 v[4:7], v[144:147], v[210:213], v[4:7]
	v_mfma_f32_16x16x32_bf16 v[4:7], v[148:151], v[214:217], v[4:7]
	v_mfma_f32_16x16x32_bf16 v[0:3], v[152:155], v[210:213], v[0:3]
	v_mfma_f32_16x16x32_bf16 v[0:3], v[156:159], v[214:217], v[0:3]
	s_setprio 0
	s_barrier
; #define PG8_STAGE(bufoff, gbase, voff) do { _Pragma("unroll") for (int _i = 0; _i < 2; ++_i) \
;         __builtin_amdgcn_global_load_lds((const unsigned*)((const char*)(gbase) + (voff)[_i]), (PG8_LAS unsigned*)(lds + (bufoff) + ldsw + _i * 8192), 16, 0, 0); } while (0)
; #define PG8_LDA(dst, b, h) do { _Pragma("unroll") for (int m = 0; m < 4; ++m) _Pragma("unroll") for (int k = 0; k < 2; ++k) dst[m][k] = *(const PG8_LAS bf16x8*)(lds + PG8_SA(b, h) + aoff + m * 2048 + k * 1024); } while (0)
; #define PG8_LDB(dst, b, h) do { _Pragma("unroll") for (int n = 0; n < 2; ++n) _Pragma("unroll") for (int k = 0; k < 2; ++k) dst[n][k] = *(const PG8_LAS bf16x8*)(lds + PG8_SB(b, h) + boff + n * 2048 + k * 1024); } while (0)
; #define PG8_MMA(ai, bj, At, Bt) do { __builtin_amdgcn_s_setprio(1); _Pragma("unroll") for (int m = 0; m < 4; ++m) _Pragma("unroll") for (int n = 0; n < 2; ++n) _Pragma("unroll") for (int k = 0; k < 2; ++k) \
;         acc[ai][bj][m][n] = __builtin_amdgcn_mfma_f32_16x16x32_bf16(Bt[n][k], At[m][k], acc[ai][bj][m][n], 0, 0, 0); __builtin_amdgcn_s_setprio(0); } while (0)
; #define PG8_WAIT_V(n) asm volatile("s_waitcnt vmcnt(" #n ")" ::: "memory")
; #define PG8_WAIT_L(n) asm volatile("s_waitcnt lgkmcnt(" #n ")" ::: "memory")
; #define PG8_BAR __builtin_amdgcn_s_barrier()
; #define PG8_SCHED __builtin_amdgcn_sched_barrier(0)
; template <class Epi, class Sched, bool ALIGN_EPI = false, bool SP2 = false>
; __device__ __forceinline__ void gemm_phase(PG8_LAS unsigned char* lds, const Gemm g, const Sched& S, const Epi& E) {
;     ...
;             PG8_LDB(B0, 1, 0); PG8_LDB(B1, 1, 1); PG8_SCHED; PG8_LDA(At, 1, 0); PG8_STAGE(PG8_SA(0, 1), a2 + hstep, voffA);
;             PG8_WAIT_V(8); PG8_WAIT_L(0); PG8_BAR; PG8_MMA(0, 0, At, B0); PG8_MMA(0, 1, At, B1); PG8_BAR; PG8_SCHED;
	s_add_i32 s36, 0, 0x18000
	s_add_i32 s37, 0, 0x1c000
	ds_read_b128 v[128:131], v218 offset:32768
	ds_read_b128 v[132:135], v218 offset:33792
	ds_read_b128 v[136:139], v218 offset:34816
	ds_read_b128 v[140:143], v218 offset:35840
	ds_read_b128 v[144:147], v218 offset:49152
	ds_read_b128 v[148:151], v218 offset:50176
	ds_read_b128 v[152:155], v218 offset:51200
	ds_read_b128 v[156:159], v218 offset:52224
	s_add_u32 s62, s62, 0x80000
	s_addc_u32 s63, s63, 0
	s_mov_b32 m0, s72
	ds_read_b128 v[174:177], v204 offset:32768
	ds_read_b128 v[178:181], v204 offset:33792
	ds_read_b128 v[182:185], v204 offset:34816
	ds_read_b128 v[194:197], v204 offset:35840
	ds_read_b128 v[198:201], v204 offset:36864
	ds_read_b128 v[206:209], v204 offset:37888
	ds_read_b128 v[210:213], v204 offset:38912
	ds_read_b128 v[214:217], v204 offset:39936
	global_load_lds_dwordx4 v160, s[62:63]
	s_mov_b32 m0, s73
	s_nop 0
	global_load_lds_dwordx4 v162, s[62:63]
	s_waitcnt vmcnt(8)
	s_waitcnt lgkmcnt(0)
	s_barrier
	s_setprio 1
	s_waitcnt lgkmcnt(0)
	v_mfma_f32_16x16x32_bf16 v[124:127], v[128:131], v[174:177], v[124:127]
	v_mfma_f32_16x16x32_bf16 v[124:127], v[132:135], v[178:181], v[124:127]
	v_mfma_f32_16x16x32_bf16 v[120:123], v[136:139], v[174:177], v[120:123]
	v_mfma_f32_16x16x32_bf16 v[120:123], v[140:143], v[178:181], v[120:123]
	v_mfma_f32_16x16x32_bf16 v[108:111], v[128:131], v[182:185], v[108:111]
	v_mfma_f32_16x16x32_bf16 v[108:111], v[132:135], v[194:197], v[108:111]
	v_mfma_f32_16x16x32_bf16 v[104:107], v[136:139], v[182:185], v[104:107]
	v_mfma_f32_16x16x32_bf16 v[104:107], v[140:143], v[194:197], v[104:107]
	v_mfma_f32_16x16x32_bf16 v[92:95], v[128:131], v[198:201], v[92:95]
	v_mfma_f32_16x16x32_bf16 v[92:95], v[132:135], v[206:209], v[92:95]
	v_mfma_f32_16x16x32_bf16 v[88:91], v[136:139], v[198:201], v[88:91]
	v_mfma_f32_16x16x32_bf16 v[88:91], v[140:143], v[206:209], v[88:91]
	v_mfma_f32_16x16x32_bf16 v[76:79], v[128:131], v[210:213], v[76:79]
	v_mfma_f32_16x16x32_bf16 v[76:79], v[132:135], v[214:217], v[76:79]
	v_mfma_f32_16x16x32_bf16 v[72:75], v[136:139], v[210:213], v[72:75]
	v_mfma_f32_16x16x32_bf16 v[72:75], v[140:143], v[214:217], v[72:75]
	v_mfma_f32_16x16x32_bf16 v[116:119], v[144:147], v[174:177], v[116:119]
	v_mfma_f32_16x16x32_bf16 v[116:119], v[148:151], v[178:181], v[116:119]
	v_mfma_f32_16x16x32_bf16 v[112:115], v[152:155], v[174:177], v[112:115]
	v_mfma_f32_16x16x32_bf16 v[112:115], v[156:159], v[178:181], v[112:115]
	v_mfma_f32_16x16x32_bf16 v[100:103], v[144:147], v[182:185], v[100:103]
	v_mfma_f32_16x16x32_bf16 v[100:103], v[148:151], v[194:197], v[100:103]
	v_mfma_f32_16x16x32_bf16 v[96:99], v[152:155], v[182:185], v[96:99]
	v_mfma_f32_16x16x32_bf16 v[96:99], v[156:159], v[194:197], v[96:99]
	v_mfma_f32_16x16x32_bf16 v[84:87], v[144:147], v[198:201], v[84:87]
	v_mfma_f32_16x16x32_bf16 v[84:87], v[148:151], v[206:209], v[84:87]
	v_mfma_f32_16x16x32_bf16 v[80:83], v[152:155], v[198:201], v[80:83]
	v_mfma_f32_16x16x32_bf16 v[80:83], v[156:159], v[206:209], v[80:83]
	v_mfma_f32_16x16x32_bf16 v[68:71], v[144:147], v[210:213], v[68:71]
	v_mfma_f32_16x16x32_bf16 v[68:71], v[148:151], v[214:217], v[68:71]
	v_mfma_f32_16x16x32_bf16 v[64:67], v[152:155], v[210:213], v[64:67]
	v_mfma_f32_16x16x32_bf16 v[64:67], v[156:159], v[214:217], v[64:67]
	s_setprio 0
	s_barrier
; #define PG8_STAGE(bufoff, gbase, voff) do { _Pragma("unroll") for (int _i = 0; _i < 2; ++_i) \
;         __builtin_amdgcn_global_load_lds((const unsigned*)((const char*)(gbase) + (voff)[_i]), (PG8_LAS unsigned*)(lds + (bufoff) + ldsw + _i * 8192), 16, 0, 0); } while (0)
; #define PG8_LDA(dst, b, h) do { _Pragma("unroll") for (int m = 0; m < 4; ++m) _Pragma("unroll") for (int k = 0; k < 2; ++k) dst[m][k] = *(const PG8_LAS bf16x8*)(lds + PG8_SA(b, h) + aoff + m * 2048 + k * 1024); } while (0)
; #define PG8_MMA(ai, bj, At, Bt) do { __builtin_amdgcn_s_setprio(1); _Pragma("unroll") for (int m = 0; m < 4; ++m) _Pragma("unroll") for (int n = 0; n < 2; ++n) _Pragma("unroll") for (int k = 0; k < 2; ++k) \
;         acc[ai][bj][m][n] = __builtin_amdgcn_mfma_f32_16x16x32_bf16(Bt[n][k], At[m][k], acc[ai][bj][m][n], 0, 0, 0); __builtin_amdgcn_s_setprio(0); } while (0)
; #define PG8_WAIT_V(n) asm volatile("s_waitcnt vmcnt(" #n ")" ::: "memory")
; #define PG8_WAIT_L(n) asm volatile("s_waitcnt lgkmcnt(" #n ")" ::: "memory")
; #define PG8_BAR __builtin_amdgcn_s_barrier()
; #define PG8_SCHED __builtin_amdgcn_sched_barrier(0)
;     __device__ __forceinline__ void operator()(const f32x4 (&acc)[2][2][4][2], const Unit& u, int wr, int wc, int fr, int fq) const {
;         const int pn = u.pn, r0 = u.pm * BM + wr * 64 + fr;
;         float rstd[2][4];
; #pragma unroll
;         for (int ai = 0; ai < 2; ++ai)
; #pragma unroll
;             for (int m = 0; m < 4; ++m) rstd[ai][m] = (float)ss[r0 + ai * HALF + m * 16] * (1.f / 16777216.f);
; template <class Epi, class Sched, bool ALIGN_EPI = false, bool SP2 = false>
; __device__ __forceinline__ void gemm_phase(PG8_LAS unsigned char* lds, const Gemm g, const Sched& S, const Epi& E) {
;     ...
;             PG8_LDA(At, 1, 1); PG8_STAGE(PG8_SB(1, 0), b3, voffB); PG8_STAGE(PG8_SB(1, 1), b3 + hstep, voffB); PG8_STAGE(PG8_SA(1, 0), a3, voffA);
;             PG8_WAIT_V(8); PG8_WAIT_L(0); PG8_BAR; PG8_MMA(1, 0, At, B0); PG8_MMA(1, 1, At, B1); PG8_BAR; PG8_SCHED;
	s_add_i32 s36, s36, s70
	s_mov_b32 m0, s36
	ds_read_b128 v[174:177], v204 offset:49152
	ds_read_b128 v[178:181], v204 offset:50176
	ds_read_b128 v[182:185], v204 offset:51200
	ds_read_b128 v[194:197], v204 offset:52224
	ds_read_b128 v[198:201], v204 offset:53248
	ds_read_b128 v[206:209], v204 offset:54272
	ds_read_b128 v[210:213], v204 offset:55296
	ds_read_b128 v[214:217], v204 offset:56320
	s_add_u32 s100, s10, 0x80
	s_addc_u32 s101, s11, 0
	global_load_lds_dwordx4 v160, s[100:101]
	s_add_i32 m0, s36, 0x2000
	s_add_u32 s10, s10, 0x80080
	s_addc_u32 s11, s11, 0
	s_add_i32 s36, s37, s70
	s_add_u32 s100, s10, 0xfff80000
	s_addc_u32 s101, s11, -1
	global_load_lds_dwordx4 v162, s[100:101]
	s_mov_b32 m0, s36
	s_nop 0
	global_load_lds_dwordx4 v160, s[10:11]
	s_add_i32 m0, s36, 0x2000
	s_nop 0
	global_load_lds_dwordx4 v162, s[10:11]
	s_mov_b32 m0, s76
	s_nop 0
	s_add_u32 s100, s62, 0xfff80080
	s_addc_u32 s101, s63, -1
	global_load_lds_dwordx4 v160, s[100:101]
	s_mov_b32 m0, s77
	s_nop 0
	global_load_lds_dwordx4 v162, s[100:101]
	s_waitcnt vmcnt(8)
	s_waitcnt lgkmcnt(0)
	s_barrier
	s_setprio 1
	s_waitcnt lgkmcnt(0)
	v_mfma_f32_16x16x32_bf16 v[60:63], v[128:131], v[174:177], v[60:63]
	v_mfma_f32_16x16x32_bf16 v[60:63], v[132:135], v[178:181], v[60:63]
	v_mfma_f32_16x16x32_bf16 v[56:59], v[136:139], v[174:177], v[56:59]
	v_mfma_f32_16x16x32_bf16 v[56:59], v[140:143], v[178:181], v[56:59]
	v_mfma_f32_16x16x32_bf16 v[44:47], v[128:131], v[182:185], v[44:47]
	v_mfma_f32_16x16x32_bf16 v[44:47], v[132:135], v[194:197], v[44:47]
	v_mfma_f32_16x16x32_bf16 v[40:43], v[136:139], v[182:185], v[40:43]
	v_mfma_f32_16x16x32_bf16 v[40:43], v[140:143], v[194:197], v[40:43]
	v_mfma_f32_16x16x32_bf16 v[28:31], v[128:131], v[198:201], v[28:31]
	v_mfma_f32_16x16x32_bf16 v[28:31], v[132:135], v[206:209], v[28:31]
	v_mfma_f32_16x16x32_bf16 v[24:27], v[136:139], v[198:201], v[24:27]
	v_mfma_f32_16x16x32_bf16 v[24:27], v[140:143], v[206:209], v[24:27]
	v_mfma_f32_16x16x32_bf16 v[12:15], v[128:131], v[210:213], v[12:15]
	v_mfma_f32_16x16x32_bf16 v[12:15], v[132:135], v[214:217], v[12:15]
	v_mfma_f32_16x16x32_bf16 v[8:11], v[136:139], v[210:213], v[8:11]
	v_mfma_f32_16x16x32_bf16 v[8:11], v[140:143], v[214:217], v[8:11]
	v_mfma_f32_16x16x32_bf16 v[52:55], v[144:147], v[174:177], v[52:55]
	v_mfma_f32_16x16x32_bf16 v[52:55], v[148:151], v[178:181], v[52:55]
	v_mfma_f32_16x16x32_bf16 v[48:51], v[152:155], v[174:177], v[48:51]
	v_mfma_f32_16x16x32_bf16 v[48:51], v[156:159], v[178:181], v[48:51]
	v_mfma_f32_16x16x32_bf16 v[36:39], v[144:147], v[182:185], v[36:39]
	v_mfma_f32_16x16x32_bf16 v[36:39], v[148:151], v[194:197], v[36:39]
	v_mfma_f32_16x16x32_bf16 v[32:35], v[152:155], v[182:185], v[32:35]
	v_mfma_f32_16x16x32_bf16 v[32:35], v[156:159], v[194:197], v[32:35]
	v_mfma_f32_16x16x32_bf16 v[20:23], v[144:147], v[198:201], v[20:23]
	v_mfma_f32_16x16x32_bf16 v[20:23], v[148:151], v[206:209], v[20:23]
	v_mfma_f32_16x16x32_bf16 v[16:19], v[152:155], v[198:201], v[16:19]
	v_mfma_f32_16x16x32_bf16 v[16:19], v[156:159], v[206:209], v[16:19]
	v_mfma_f32_16x16x32_bf16 v[4:7], v[144:147], v[210:213], v[4:7]
	v_mfma_f32_16x16x32_bf16 v[4:7], v[148:151], v[214:217], v[4:7]
	v_mfma_f32_16x16x32_bf16 v[0:3], v[152:155], v[210:213], v[0:3]
	v_mfma_f32_16x16x32_bf16 v[0:3], v[156:159], v[214:217], v[0:3]
	s_setprio 0
	s_barrier
	s_add_i32 s57, s57, 2
	s_add_u32 s8, s8, 0x100
	s_addc_u32 s9, s9, 0
	s_add_u32 s55, s55, 0x100
	s_addc_u32 s3, s3, 0
	s_cmp_gt_u32 s57, 29
	s_cbranch_scc0 .LBB0_344
	s_lshl_b32 s57, s6, 8
	s_add_i32 s57, s57, s75
	v_or_b32_e32 v178, s57, v165
	v_ashrrev_i32_e32 v179, 31, v178
	v_lshl_add_u64 v[128:129], v[178:179], 3, s[92:93]
	global_load_dwordx2 v[130:131], v[128:129], off
	global_load_dwordx2 v[132:133], v[128:129], off offset:128
	global_load_dwordx2 v[134:135], v[128:129], off offset:256
	global_load_dwordx2 v[136:137], v[128:129], off offset:384
	global_load_dwordx2 v[138:139], v[128:129], off offset:1024
	global_load_dwordx2 v[140:141], v[128:129], off offset:1152
	global_load_dwordx2 v[142:143], v[128:129], off offset:1280
	global_load_dwordx2 v[144:145], v[128:129], off offset:1408
	s_and_b64 vcc, exec, s[12:13]
	s_cbranch_vccz .LBB0_347
	s_barrier
